# nt policy on the LDS-coalesced epilogue stores (y_hg, MERGE, RES1, PLE outputs: full 512-B rows, once-written streams)
# baseline (speedup 1.0000x reference)
; #define LAS __attribute__((address_space(3)))
;     __device__ __forceinline__ void stage512(const u32x4 a, const u32x4 b, unsigned char* g0, size_t ldb, int wr, int wc, int fr, int fq) const {
;         LAS unsigned char* sb = lds + LDS_STG + wr * 8448;
;         *(LAS u32x4*)(sb + fr * 528 + wc * 64 + fq * 16) = a; *(LAS u32x4*)(sb + fr * 528 + 256 + wc * 64 + fq * 16) = b;
;         asm volatile("s_waitcnt lgkmcnt(0)" ::: "memory"); __builtin_amdgcn_s_barrier(); asm volatile("" ::: "memory");
;         const int l = fq * 16 + fr;
; #pragma unroll
;         for (int q = 0; q < 2; ++q) { const int rl = (q * 4 + wc) * 2 + (l >> 5); const u32x4 v = *(const LAS u32x4*)(sb + rl * 528 + (l & 31) * 16); *(u32x4*)(g0 + (size_t)rl * ldb + (l & 31) * 16) = v; }
;         asm volatile("s_waitcnt lgkmcnt(0)" ::: "memory"); __builtin_amdgcn_s_barrier(); asm volatile("" ::: "memory");
;     __device__ __forceinline__ float compute(const Pre& p, f32x4 (&acc)[2][2][4][2], const f32x4 (&cv)[2][2], const pg8::Unit& u, int ai, int m, int wr, int wc, int fr, int fq) const {
;     ...
;         if (MODE == EM_PLAIN) stage512(pk[0], pk[1], (unsigned char*)O + (trow * ldc + u.pn * 256) * 2, (size_t)ldc * 2, wr, wc, fr, fq);
.LBB0_963:
	s_lshl_b32 s15, s22, 8
	s_lshl_b32 s24, s23, 8
	s_add_i32 s22, s15, s44
	s_ashr_i32 s25, s24, 31
	v_cvt_pk_bf16_f32 v124, v124, v125
	v_cvt_pk_bf16_f32 v125, v126, v127
	v_cvt_pk_bf16_f32 v126, v120, v121
	v_cvt_pk_bf16_f32 v127, v122, v123
	s_ashr_i32 s23, s22, 31
	v_cvt_pk_bf16_f32 v116, v116, v117
	v_cvt_pk_bf16_f32 v117, v118, v119
	v_cvt_pk_bf16_f32 v118, v112, v113
	v_cvt_pk_bf16_f32 v119, v114, v115
	s_lshl_b64 s[26:27], s[22:23], 11
	s_lshl_b64 s[24:25], s[24:25], 1
	ds_write_b128 v154, v[124:127]
	ds_write_b128 v154, v[116:119] offset:256
	s_add_u32 s15, s42, s26
	s_waitcnt lgkmcnt(0)
	s_barrier
	s_addc_u32 s17, s43, s27
	ds_read_b128 v[112:115], v155
	ds_read_b128 v[116:119], v155 offset:4224
	s_add_u32 s26, s15, s24
	s_addc_u32 s27, s17, s25
	v_lshl_add_u64 v[120:121], s[26:27], 0, v[136:137]
	v_lshl_add_u64 v[122:123], v[120:121], 0, v[138:139]
	s_waitcnt lgkmcnt(0)
	global_store_dwordx4 v[122:123], v[112:115], off nt
	s_or_b32 s26, s22, 16
	v_cvt_pk_bf16_f32 v108, v108, v109
	v_lshl_add_u64 v[112:113], v[120:121], 0, v[140:141]
	global_store_dwordx4 v[112:113], v[116:119], off nt
	v_cvt_pk_bf16_f32 v109, v110, v111
	v_cvt_pk_bf16_f32 v110, v104, v105
	v_cvt_pk_bf16_f32 v111, v106, v107
	s_ashr_i32 s27, s26, 31
	s_waitcnt lgkmcnt(0)
	s_barrier
	v_cvt_pk_bf16_f32 v100, v100, v101
	v_cvt_pk_bf16_f32 v101, v102, v103
	v_cvt_pk_bf16_f32 v102, v96, v97
	v_cvt_pk_bf16_f32 v103, v98, v99
	s_lshl_b64 s[26:27], s[26:27], 11
	ds_write_b128 v154, v[108:111]
	ds_write_b128 v154, v[100:103] offset:256
	s_add_u32 s15, s42, s26
	s_waitcnt lgkmcnt(0)
	s_barrier
	s_addc_u32 s17, s43, s27
	ds_read_b128 v[96:99], v155
	ds_read_b128 v[100:103], v155 offset:4224
	s_add_u32 s26, s15, s24
	s_addc_u32 s27, s17, s25
	v_lshl_add_u64 v[104:105], s[26:27], 0, v[136:137]
	v_lshl_add_u64 v[106:107], v[104:105], 0, v[138:139]
	s_waitcnt lgkmcnt(0)
	global_store_dwordx4 v[106:107], v[96:99], off nt
	s_or_b32 s26, s22, 32
	v_cvt_pk_bf16_f32 v92, v92, v93
	v_lshl_add_u64 v[96:97], v[104:105], 0, v[140:141]
	global_store_dwordx4 v[96:97], v[100:103], off nt
	v_cvt_pk_bf16_f32 v93, v94, v95
	v_cvt_pk_bf16_f32 v94, v88, v89
	v_cvt_pk_bf16_f32 v95, v90, v91
	s_ashr_i32 s27, s26, 31
	s_waitcnt lgkmcnt(0)
	s_barrier
	v_cvt_pk_bf16_f32 v84, v84, v85
	v_cvt_pk_bf16_f32 v85, v86, v87
	v_cvt_pk_bf16_f32 v86, v80, v81
	v_cvt_pk_bf16_f32 v87, v82, v83
	s_lshl_b64 s[26:27], s[26:27], 11
	ds_write_b128 v154, v[92:95]
	ds_write_b128 v154, v[84:87] offset:256
	s_add_u32 s15, s42, s26
	s_waitcnt lgkmcnt(0)
	s_barrier
	s_addc_u32 s17, s43, s27
	ds_read_b128 v[80:83], v155
	ds_read_b128 v[84:87], v155 offset:4224
	s_add_u32 s26, s15, s24
	s_addc_u32 s27, s17, s25
	v_lshl_add_u64 v[88:89], s[26:27], 0, v[136:137]
	v_lshl_add_u64 v[90:91], v[88:89], 0, v[138:139]
	s_waitcnt lgkmcnt(0)
	global_store_dwordx4 v[90:91], v[80:83], off nt
	s_or_b32 s26, s22, 48
	v_cvt_pk_bf16_f32 v76, v76, v77
	v_lshl_add_u64 v[80:81], v[88:89], 0, v[140:141]
	global_store_dwordx4 v[80:81], v[84:87], off nt
	v_cvt_pk_bf16_f32 v77, v78, v79
	v_cvt_pk_bf16_f32 v78, v72, v73
	v_cvt_pk_bf16_f32 v79, v74, v75
	s_ashr_i32 s27, s26, 31
	s_waitcnt lgkmcnt(0)
	s_barrier
	v_cvt_pk_bf16_f32 v68, v68, v69
	v_cvt_pk_bf16_f32 v69, v70, v71
	v_cvt_pk_bf16_f32 v70, v64, v65
	v_cvt_pk_bf16_f32 v71, v66, v67
	s_lshl_b64 s[26:27], s[26:27], 11
	ds_write_b128 v154, v[76:79]
	ds_write_b128 v154, v[68:71] offset:256
	s_add_u32 s15, s42, s26
	s_waitcnt lgkmcnt(0)
	s_barrier
	s_addc_u32 s17, s43, s27
	ds_read_b128 v[64:67], v155
	ds_read_b128 v[68:71], v155 offset:4224
	s_add_u32 s26, s15, s24
	s_addc_u32 s27, s17, s25
	v_lshl_add_u64 v[72:73], s[26:27], 0, v[136:137]
	v_lshl_add_u64 v[74:75], v[72:73], 0, v[138:139]
	s_waitcnt lgkmcnt(0)
	global_store_dwordx4 v[74:75], v[64:67], off nt
	s_add_i32 s26, s22, 0x80
	v_cvt_pk_bf16_f32 v60, v60, v61
	v_lshl_add_u64 v[64:65], v[72:73], 0, v[140:141]
	global_store_dwordx4 v[64:65], v[68:71], off nt
	v_cvt_pk_bf16_f32 v61, v62, v63
	v_cvt_pk_bf16_f32 v62, v56, v57
	v_cvt_pk_bf16_f32 v63, v58, v59
	s_ashr_i32 s27, s26, 31
	s_waitcnt lgkmcnt(0)
	s_barrier
; #define LAS __attribute__((address_space(3)))
;     __device__ __forceinline__ void stage512(const u32x4 a, const u32x4 b, unsigned char* g0, size_t ldb, int wr, int wc, int fr, int fq) const {
;         LAS unsigned char* sb = lds + LDS_STG + wr * 8448;
;         *(LAS u32x4*)(sb + fr * 528 + wc * 64 + fq * 16) = a; *(LAS u32x4*)(sb + fr * 528 + 256 + wc * 64 + fq * 16) = b;
;         asm volatile("s_waitcnt lgkmcnt(0)" ::: "memory"); __builtin_amdgcn_s_barrier(); asm volatile("" ::: "memory");
;         const int l = fq * 16 + fr;
; #pragma unroll
;         for (int q = 0; q < 2; ++q) { const int rl = (q * 4 + wc) * 2 + (l >> 5); const u32x4 v = *(const LAS u32x4*)(sb + rl * 528 + (l & 31) * 16); *(u32x4*)(g0 + (size_t)rl * ldb + (l & 31) * 16) = v; }
;         asm volatile("s_waitcnt lgkmcnt(0)" ::: "memory"); __builtin_amdgcn_s_barrier(); asm volatile("" ::: "memory");
;     __device__ __forceinline__ float compute(const Pre& p, f32x4 (&acc)[2][2][4][2], const f32x4 (&cv)[2][2], const pg8::Unit& u, int ai, int m, int wr, int wc, int fr, int fq) const {
;     ...
;         if (MODE == EM_PLAIN) stage512(pk[0], pk[1], (unsigned char*)O + (trow * ldc + u.pn * 256) * 2, (size_t)ldc * 2, wr, wc, fr, fq);
	v_cvt_pk_bf16_f32 v52, v52, v53
	v_cvt_pk_bf16_f32 v53, v54, v55
	v_cvt_pk_bf16_f32 v54, v48, v49
	v_cvt_pk_bf16_f32 v55, v50, v51
	s_lshl_b64 s[26:27], s[26:27], 11
	ds_write_b128 v154, v[60:63]
	ds_write_b128 v154, v[52:55] offset:256
	s_add_u32 s15, s42, s26
	s_waitcnt lgkmcnt(0)
	s_barrier
	s_addc_u32 s17, s43, s27
	ds_read_b128 v[48:51], v155
	ds_read_b128 v[52:55], v155 offset:4224
	s_add_u32 s26, s15, s24
	s_addc_u32 s27, s17, s25
	v_lshl_add_u64 v[56:57], s[26:27], 0, v[136:137]
	v_lshl_add_u64 v[58:59], v[56:57], 0, v[138:139]
	s_waitcnt lgkmcnt(0)
	global_store_dwordx4 v[58:59], v[48:51], off nt
	s_add_i32 s26, s22, 0x90
	v_cvt_pk_bf16_f32 v44, v44, v45
	v_lshl_add_u64 v[48:49], v[56:57], 0, v[140:141]
	global_store_dwordx4 v[48:49], v[52:55], off nt
	v_cvt_pk_bf16_f32 v45, v46, v47
	v_cvt_pk_bf16_f32 v46, v40, v41
	v_cvt_pk_bf16_f32 v47, v42, v43
	s_ashr_i32 s27, s26, 31
	s_waitcnt lgkmcnt(0)
	s_barrier
	v_cvt_pk_bf16_f32 v36, v36, v37
	v_cvt_pk_bf16_f32 v37, v38, v39
	v_cvt_pk_bf16_f32 v38, v32, v33
	v_cvt_pk_bf16_f32 v39, v34, v35
	s_lshl_b64 s[26:27], s[26:27], 11
	ds_write_b128 v154, v[44:47]
	ds_write_b128 v154, v[36:39] offset:256
	s_add_u32 s15, s42, s26
	s_waitcnt lgkmcnt(0)
	s_barrier
	s_addc_u32 s17, s43, s27
	ds_read_b128 v[32:35], v155
	ds_read_b128 v[36:39], v155 offset:4224
	s_add_u32 s26, s15, s24
	s_addc_u32 s27, s17, s25
	v_lshl_add_u64 v[40:41], s[26:27], 0, v[136:137]
	v_lshl_add_u64 v[42:43], v[40:41], 0, v[138:139]
	s_waitcnt lgkmcnt(0)
	global_store_dwordx4 v[42:43], v[32:35], off nt
	s_add_i32 s26, s22, 0xa0
	v_cvt_pk_bf16_f32 v28, v28, v29
	v_lshl_add_u64 v[32:33], v[40:41], 0, v[140:141]
	global_store_dwordx4 v[32:33], v[36:39], off nt
	v_cvt_pk_bf16_f32 v29, v30, v31
	v_cvt_pk_bf16_f32 v30, v24, v25
	v_cvt_pk_bf16_f32 v31, v26, v27
	s_ashr_i32 s27, s26, 31
	s_waitcnt lgkmcnt(0)
	s_barrier
	v_cvt_pk_bf16_f32 v20, v20, v21
	v_cvt_pk_bf16_f32 v21, v22, v23
	v_cvt_pk_bf16_f32 v22, v16, v17
	v_cvt_pk_bf16_f32 v23, v18, v19
	s_lshl_b64 s[26:27], s[26:27], 11
	ds_write_b128 v154, v[28:31]
	ds_write_b128 v154, v[20:23] offset:256
	s_add_u32 s15, s42, s26
	s_waitcnt lgkmcnt(0)
	s_barrier
	s_addc_u32 s17, s43, s27
	ds_read_b128 v[16:19], v155
	ds_read_b128 v[20:23], v155 offset:4224
	s_add_u32 s26, s15, s24
	s_addc_u32 s27, s17, s25
	v_lshl_add_u64 v[24:25], s[26:27], 0, v[136:137]
	v_lshl_add_u64 v[26:27], v[24:25], 0, v[138:139]
	s_waitcnt lgkmcnt(0)
	global_store_dwordx4 v[26:27], v[16:19], off nt
	s_addk_i32 s22, 0xb0
	v_cvt_pk_bf16_f32 v12, v12, v13
	v_lshl_add_u64 v[16:17], v[24:25], 0, v[140:141]
	global_store_dwordx4 v[16:17], v[20:23], off nt
	v_cvt_pk_bf16_f32 v13, v14, v15
	v_cvt_pk_bf16_f32 v14, v8, v9
	v_cvt_pk_bf16_f32 v15, v10, v11
	s_ashr_i32 s23, s22, 31
	s_waitcnt lgkmcnt(0)
	s_barrier
	v_cvt_pk_bf16_f32 v4, v4, v5
	v_cvt_pk_bf16_f32 v5, v6, v7
	v_cvt_pk_bf16_f32 v6, v0, v1
	v_cvt_pk_bf16_f32 v7, v2, v3
	s_lshl_b64 s[22:23], s[22:23], 11
	ds_write_b128 v154, v[12:15]
	ds_write_b128 v154, v[4:7] offset:256
	s_add_u32 s15, s42, s22
	s_waitcnt lgkmcnt(0)
	s_barrier
	s_addc_u32 s17, s43, s23
	ds_read_b128 v[0:3], v155
	ds_read_b128 v[4:7], v155 offset:4224
	s_add_u32 s22, s15, s24
	s_addc_u32 s23, s17, s25
	v_lshl_add_u64 v[8:9], s[22:23], 0, v[136:137]
	v_lshl_add_u64 v[10:11], v[8:9], 0, v[138:139]
	s_waitcnt lgkmcnt(0)
	global_store_dwordx4 v[10:11], v[0:3], off nt
	s_andn2_b64 vcc, exec, s[4:5]
	s_mov_b64 s[4:5], -1
	v_lshl_add_u64 v[0:1], v[8:9], 0, v[140:141]
	global_store_dwordx4 v[0:1], v[4:7], off nt
	s_waitcnt lgkmcnt(0)
	s_barrier
	s_cbranch_vccnz .LBB0_952
	s_andn2_b64 vcc, exec, s[6:7]
	s_cbranch_vccnz .LBB0_951
	s_barrier
	s_branch .LBB0_951

; __device__ __forceinline__ u32x4 pack8(const float (&f)[8]) { u32x4 w; w.x = pk2(f[0], f[1]); w.y = pk2(f[2], f[3]); w.z = pk2(f[4], f[5]); w.w = pk2(f[6], f[7]); return w; }
;     __device__ __forceinline__ void load(Pre& p, const pg8::Unit& u, int ai, int m, int wr, int wc, int fr, int fq) const {
;         const int row = u.pm * 256 + ai * 128 + wr * 64 + m * 16 + fr;
;         if (MODE == EM_PROJ || MODE == EM_GATES) p.rs = ((const float*)(ws + WS_RINV0))[row];
;         if (MODE == EM_RES2) p.rs = ((const float*)(ws + WS_SS1))[row];
; #pragma unroll
;         for (int bj = 0; bj < 2; ++bj) {
;             const int ct = bj * 128 + wc * 32 + fq * 8; const size_t o = (size_t)row * 1024 + u.pn * 256 + ct;
;             if (MODE == EM_MERGE) { const unsigned char* g8 = ws + WS_G8 + (size_t)row * 2048 + u.pn * 256 + ct; const u32x2 ga = *(const u32x2*)g8, gc = *(const u32x2*)(g8 + 1024);
;                 p.a[bj] = (u32x4){ga.x, ga.y, gc.x, gc.y}; p.b[bj] = *(const u32x4*)((const bf16_t*)(ws + WS_YHG) + o); }
;             if (MODE == EM_RES1) p.a[bj] = *(const u32x4*)((const bf16_t*)(ws + WS_XB) + o);
;             if (MODE == EM_RES2) { p.b[bj] = *(const u32x4*)((const bf16_t*)(ws + WS_H1B) + o); p.a[bj] = *(const u32x4*)((const bf16_t*)(ws + WS_PE) + o); }
;             if (MODE == EM_GLU && bj == 0) p.a[0] = *(const u32x4*)((const bf16_t*)(ws + WS_ZS) + (size_t)row * 512 + u.pn * 128 + wc * 32 + fq * 8);
;         }
;     }
;     __device__ __forceinline__ float compute(const Pre& p, f32x4 (&acc)[2][2][4][2], const f32x4 (&cv)[2][2], const pg8::Unit& u, int ai, int m, int wr, int wc, int fr, int fq) const {
;     ...
;             } else if (MODE == EM_MERGE) {
;                 const size_t o = (size_t)row * 1024 + u.pn * 256 + ct;
;                 float b[8]; unpack8(p.b[bj], b);
;                 float w[8];
; #pragma unroll
;                 for (int j = 0; j < 8; ++j) { const unsigned wa = j < 4 ? p.a[bj].x : p.a[bj].y, wc2 = j < 4 ? p.a[bj].z : p.a[bj].w; const int sh = 8 * (j & 3);
;                     const float ga = (float)((wa >> sh) & 255u) * (1.0f / 255.0f), gc = (float)((wc2 >> sh) & 255u) * (1.0f / 255.0f); w[j] = ga * b[j] + gc * v[j]; }
;                 pk[bj] = pack8(w); (void)o;
.LBB0_1149:
	s_lshl_b32 s19, s26, 8
	s_lshl_b32 s30, s27, 8
	s_add_i32 s28, s19, s43
	s_ashr_i32 s31, s30, 31
	v_or_b32_e32 v178, s28, v204
	s_lshl_b64 s[26:27], s[30:31], 1
	s_add_u32 s30, s46, s30
	v_ashrrev_i32_e32 v179, 31, v178
	s_addc_u32 s31, s47, s31
	v_lshlrev_b64 v[128:129], 11, v[178:179]
	v_lshl_add_u64 v[130:131], s[30:31], 0, v[128:129]
	s_add_u32 s34, s48, s26
	v_lshl_add_u64 v[130:131], v[130:131], 0, v[162:163]
	s_addc_u32 s35, s49, s27
	global_load_dwordx2 v[220:221], v[130:131], off
	global_load_dwordx2 v[222:223], v[130:131], off offset:1024
	v_lshl_add_u64 v[128:129], s[34:35], 0, v[128:129]
	v_lshl_add_u64 v[128:129], v[128:129], 0, v[160:161]
	global_load_dwordx4 v[212:215], v[128:129], off
	global_load_dwordx2 v[224:225], v[130:131], off offset:1152
	global_load_dwordx2 v[226:227], v[130:131], off offset:128
	global_load_dwordx4 v[216:219], v[128:129], off offset:256
	v_or_b32_e32 v132, 16, v178
	v_or_b32_e32 v134, 48, v178
	v_ashrrev_i32_e32 v133, 31, v132
	v_ashrrev_i32_e32 v135, 31, v134
	v_lshlrev_b64 v[128:129], 11, v[132:133]
	v_lshlrev_b64 v[132:133], 11, v[134:135]
	v_lshl_add_u64 v[134:135], s[30:31], 0, v[128:129]
	v_lshl_add_u64 v[134:135], v[134:135], 0, v[162:163]
	v_or_b32_e32 v130, 32, v178
	global_load_dwordx2 v[202:203], v[134:135], off
	global_load_dwordx2 v[200:201], v[134:135], off offset:1024
	global_load_dwordx2 v[196:197], v[134:135], off offset:1152
	global_load_dwordx2 v[198:199], v[134:135], off offset:128
	v_ashrrev_i32_e32 v131, 31, v130
	v_lshlrev_b64 v[130:131], 11, v[130:131]
	v_lshl_add_u64 v[136:137], s[30:31], 0, v[130:131]
	v_lshl_add_u64 v[138:139], s[30:31], 0, v[132:133]
	v_lshl_add_u64 v[128:129], s[34:35], 0, v[128:129]
	v_lshl_add_u64 v[130:131], s[34:35], 0, v[130:131]
	v_lshl_add_u64 v[136:137], v[136:137], 0, v[162:163]
	v_lshl_add_u64 v[138:139], v[138:139], 0, v[162:163]
	v_lshl_add_u64 v[132:133], s[34:35], 0, v[132:133]
	v_lshl_add_u64 v[128:129], v[128:129], 0, v[160:161]
	v_lshl_add_u64 v[130:131], v[130:131], 0, v[160:161]
	global_load_dwordx2 v[194:195], v[136:137], off
	global_load_dwordx2 v[192:193], v[136:137], off offset:1024
	global_load_dwordx2 v[188:189], v[136:137], off offset:1152
	global_load_dwordx2 v[190:191], v[136:137], off offset:128
	v_lshl_add_u64 v[228:229], v[132:133], 0, v[160:161]
	global_load_dwordx2 v[186:187], v[138:139], off
	global_load_dwordx2 v[184:185], v[138:139], off offset:1024
	global_load_dwordx2 v[180:181], v[138:139], off offset:1152
	global_load_dwordx2 v[182:183], v[138:139], off offset:128
	global_load_dwordx4 v[148:151], v[128:129], off
	global_load_dwordx4 v[144:147], v[128:129], off offset:256
	global_load_dwordx4 v[140:143], v[130:131], off
	s_nop 0
	global_load_dwordx4 v[136:139], v[130:131], off offset:256
	global_load_dwordx4 v[132:135], v[228:229], off
	s_nop 0
	global_load_dwordx4 v[128:131], v[228:229], off offset:256
	s_ashr_i32 s29, s28, 31
	s_lshl_b64 s[56:57], s[28:29], 11
	s_add_u32 s19, s50, s56
	s_addc_u32 s21, s51, s57
	s_add_u32 s56, s19, s26
	s_addc_u32 s57, s21, s27
	s_waitcnt vmcnt(0)
	v_cvt_f32_ubyte3_e32 v233, v220
	v_cvt_f32_ubyte3_e32 v235, v222
	v_cvt_f32_ubyte2_e32 v234, v222
	v_cvt_f32_ubyte2_e32 v232, v220
	v_pk_mul_f32 v[234:235], v[234:235], s[16:17] op_sel_hi:[1,0]
	v_pk_mul_f32 v[232:233], v[232:233], s[16:17] op_sel_hi:[1,0]
	v_lshlrev_b32_e32 v240, 16, v212
	v_and_b32_e32 v241, 0xffff0000, v212
	v_lshlrev_b32_e32 v212, 16, v213
	v_and_b32_e32 v213, 0xffff0000, v213
	v_pk_mul_f32 v[126:127], v[126:127], v[234:235]
	v_cvt_f32_ubyte1_e32 v229, v220
	v_cvt_f32_ubyte0_e32 v228, v220
	v_cvt_f32_ubyte1_e32 v231, v222
	v_cvt_f32_ubyte0_e32 v230, v222
	v_cvt_f32_ubyte1_e32 v237, v221
	v_cvt_f32_ubyte0_e32 v236, v221
	v_pk_fma_f32 v[126:127], v[232:233], v[212:213], v[126:127]
	v_cvt_f32_ubyte3_e32 v213, v221
	v_cvt_f32_ubyte2_e32 v212, v221
	v_cvt_f32_ubyte3_e32 v221, v223
	v_cvt_f32_ubyte2_e32 v220, v223
	v_pk_mul_f32 v[230:231], v[230:231], s[16:17] op_sel_hi:[1,0]
	v_pk_mul_f32 v[220:221], v[220:221], s[16:17] op_sel_hi:[1,0]
	v_pk_mul_f32 v[124:125], v[124:125], v[230:231]
	v_lshlrev_b32_e32 v230, 16, v214
	v_and_b32_e32 v231, 0xffff0000, v214
	v_pk_mul_f32 v[212:213], v[212:213], s[16:17] op_sel_hi:[1,0]
	v_lshlrev_b32_e32 v214, 16, v215
	v_and_b32_e32 v215, 0xffff0000, v215
	v_pk_mul_f32 v[122:123], v[122:123], v[220:221]
	v_cvt_f32_ubyte1_e32 v221, v224
	v_cvt_f32_ubyte0_e32 v220, v224
	v_pk_fma_f32 v[122:123], v[212:213], v[214:215], v[122:123]
	v_cvt_f32_ubyte1_e32 v213, v226
	v_cvt_f32_ubyte0_e32 v212, v226
	v_pk_mul_f32 v[220:221], v[220:221], s[16:17] op_sel_hi:[1,0]
	v_pk_mul_f32 v[212:213], v[212:213], s[16:17] op_sel_hi:[1,0]
	v_lshlrev_b32_e32 v214, 16, v216
	v_and_b32_e32 v215, 0xffff0000, v216
	v_pk_mul_f32 v[116:117], v[116:117], v[220:221]
	v_cvt_f32_ubyte2_e32 v216, v224
	v_pk_fma_f32 v[212:213], v[212:213], v[214:215], v[116:117]
	v_lshlrev_b32_e32 v214, 16, v217
	v_and_b32_e32 v215, 0xffff0000, v217
	v_cvt_f32_ubyte3_e32 v217, v224
	v_cvt_f32_ubyte3_e32 v117, v226
	v_cvt_f32_ubyte2_e32 v116, v226
	v_pk_mul_f32 v[216:217], v[216:217], s[16:17] op_sel_hi:[1,0]
	v_cvt_f32_ubyte1_e32 v239, v223
	v_cvt_f32_ubyte0_e32 v238, v223
	v_pk_mul_f32 v[116:117], v[116:117], s[16:17] op_sel_hi:[1,0]
	v_pk_mul_f32 v[118:119], v[118:119], v[216:217]
	v_cvt_f32_ubyte1_e32 v217, v225
	v_cvt_f32_ubyte0_e32 v216, v225
	v_pk_mul_f32 v[238:239], v[238:239], s[16:17] op_sel_hi:[1,0]
	v_pk_fma_f32 v[214:215], v[116:117], v[214:215], v[118:119]
	v_cvt_f32_ubyte1_e32 v117, v227
	v_cvt_f32_ubyte0_e32 v116, v227
	v_pk_mul_f32 v[216:217], v[216:217], s[16:17] op_sel_hi:[1,0]
	v_pk_mul_f32 v[236:237], v[236:237], s[16:17] op_sel_hi:[1,0]
	v_pk_mul_f32 v[120:121], v[120:121], v[238:239]
	v_pk_mul_f32 v[116:117], v[116:117], s[16:17] op_sel_hi:[1,0]
	v_lshlrev_b32_e32 v118, 16, v218
	v_and_b32_e32 v119, 0xffff0000, v218
	v_pk_mul_f32 v[112:113], v[112:113], v[216:217]
	v_pk_fma_f32 v[120:121], v[236:237], v[230:231], v[120:121]
	v_pk_fma_f32 v[216:217], v[116:117], v[118:119], v[112:113]
	v_cvt_pk_bf16_f32 v119, v122, v123
	v_cvt_f32_ubyte3_e32 v123, v225
	v_cvt_f32_ubyte2_e32 v122, v225
	v_pk_mul_f32 v[228:229], v[228:229], s[16:17] op_sel_hi:[1,0]
	v_cvt_pk_bf16_f32 v118, v120, v121
	v_cvt_f32_ubyte3_e32 v121, v227
	v_cvt_f32_ubyte2_e32 v120, v227
	v_pk_mul_f32 v[122:123], v[122:123], s[16:17] op_sel_hi:[1,0]
	v_pk_fma_f32 v[124:125], v[228:229], v[240:241], v[124:125]
	v_lshlrev_b32_e32 v112, 16, v219
	v_and_b32_e32 v113, 0xffff0000, v219
	v_pk_mul_f32 v[120:121], v[120:121], s[16:17] op_sel_hi:[1,0]
	v_pk_mul_f32 v[114:115], v[114:115], v[122:123]
	v_cvt_pk_bf16_f32 v116, v124, v125
	v_cvt_pk_bf16_f32 v117, v126, v127
	v_pk_fma_f32 v[120:121], v[120:121], v[112:113], v[114:115]
	v_cvt_pk_bf16_f32 v112, v212, v213
	v_cvt_pk_bf16_f32 v113, v214, v215
	v_cvt_pk_bf16_f32 v114, v216, v217
	v_cvt_pk_bf16_f32 v115, v120, v121
	ds_write_b128 v209, v[116:119]
	ds_write_b128 v209, v[112:115] offset:256
	s_waitcnt lgkmcnt(0)
	s_barrier
; #define LAS __attribute__((address_space(3)))
; __device__ __forceinline__ u32x4 pack8(const float (&f)[8]) { u32x4 w; w.x = pk2(f[0], f[1]); w.y = pk2(f[2], f[3]); w.z = pk2(f[4], f[5]); w.w = pk2(f[6], f[7]); return w; }
;     __device__ __forceinline__ void stage512(const u32x4 a, const u32x4 b, unsigned char* g0, size_t ldb, int wr, int wc, int fr, int fq) const {
;         LAS unsigned char* sb = lds + LDS_STG + wr * 8448;
;         *(LAS u32x4*)(sb + fr * 528 + wc * 64 + fq * 16) = a; *(LAS u32x4*)(sb + fr * 528 + 256 + wc * 64 + fq * 16) = b;
;         asm volatile("s_waitcnt lgkmcnt(0)" ::: "memory"); __builtin_amdgcn_s_barrier(); asm volatile("" ::: "memory");
;         const int l = fq * 16 + fr;
; #pragma unroll
;         for (int q = 0; q < 2; ++q) { const int rl = (q * 4 + wc) * 2 + (l >> 5); const u32x4 v = *(const LAS u32x4*)(sb + rl * 528 + (l & 31) * 16); *(u32x4*)(g0 + (size_t)rl * ldb + (l & 31) * 16) = v; }
;         asm volatile("s_waitcnt lgkmcnt(0)" ::: "memory"); __builtin_amdgcn_s_barrier(); asm volatile("" ::: "memory");
;     __device__ __forceinline__ float compute(const Pre& p, f32x4 (&acc)[2][2][4][2], const f32x4 (&cv)[2][2], const pg8::Unit& u, int ai, int m, int wr, int wc, int fr, int fq) const {
;     ...
;             } else if (MODE == EM_MERGE) {
;                 const size_t o = (size_t)row * 1024 + u.pn * 256 + ct;
;                 float b[8]; unpack8(p.b[bj], b);
;                 float w[8];
; #pragma unroll
;                 for (int j = 0; j < 8; ++j) { const unsigned wa = j < 4 ? p.a[bj].x : p.a[bj].y, wc2 = j < 4 ? p.a[bj].z : p.a[bj].w; const int sh = 8 * (j & 3);
;                     const float ga = (float)((wa >> sh) & 255u) * (1.0f / 255.0f), gc = (float)((wc2 >> sh) & 255u) * (1.0f / 255.0f); w[j] = ga * b[j] + gc * v[j]; }
;                 pk[bj] = pack8(w); (void)o;
	ds_read_b128 v[112:115], v210
	ds_read_b128 v[116:119], v210 offset:4224
	v_lshl_add_u64 v[120:121], s[56:57], 0, v[164:165]
	v_lshl_add_u64 v[122:123], v[120:121], 0, v[166:167]
	s_or_b32 s56, s28, 16
	s_waitcnt lgkmcnt(1)
	global_store_dwordx4 v[122:123], v[112:115], off nt
	s_ashr_i32 s57, s56, 31
	s_lshl_b64 s[56:57], s[56:57], 11
	v_lshl_add_u64 v[112:113], v[120:121], 0, v[168:169]
	s_waitcnt lgkmcnt(0)
	global_store_dwordx4 v[112:113], v[116:119], off nt
	v_cvt_f32_ubyte1_e32 v113, v202
	v_cvt_f32_ubyte0_e32 v112, v202
	v_cvt_f32_ubyte1_e32 v117, v200
	v_cvt_f32_ubyte0_e32 v116, v200
	v_pk_mul_f32 v[116:117], v[116:117], s[16:17] op_sel_hi:[1,0]
	v_pk_mul_f32 v[112:113], v[112:113], s[16:17] op_sel_hi:[1,0]
	v_lshlrev_b32_e32 v114, 16, v148
	v_and_b32_e32 v115, 0xffff0000, v148
	v_pk_mul_f32 v[108:109], v[108:109], v[116:117]
	v_cvt_f32_ubyte3_e32 v117, v200
	v_cvt_f32_ubyte2_e32 v116, v200
	v_pk_fma_f32 v[108:109], v[112:113], v[114:115], v[108:109]
	v_cvt_f32_ubyte3_e32 v113, v202
	v_cvt_f32_ubyte2_e32 v112, v202
	v_pk_mul_f32 v[116:117], v[116:117], s[16:17] op_sel_hi:[1,0]
	v_pk_mul_f32 v[112:113], v[112:113], s[16:17] op_sel_hi:[1,0]
	v_lshlrev_b32_e32 v114, 16, v149
	v_and_b32_e32 v115, 0xffff0000, v149
	v_pk_mul_f32 v[110:111], v[110:111], v[116:117]
	v_cvt_f32_ubyte1_e32 v117, v201
	v_cvt_f32_ubyte0_e32 v116, v201
	v_pk_fma_f32 v[110:111], v[112:113], v[114:115], v[110:111]
	v_cvt_f32_ubyte1_e32 v113, v203
	v_cvt_f32_ubyte0_e32 v112, v203
	v_pk_mul_f32 v[116:117], v[116:117], s[16:17] op_sel_hi:[1,0]
	v_pk_mul_f32 v[112:113], v[112:113], s[16:17] op_sel_hi:[1,0]
	v_lshlrev_b32_e32 v114, 16, v150
	v_and_b32_e32 v115, 0xffff0000, v150
	v_pk_mul_f32 v[104:105], v[104:105], v[116:117]
	v_cvt_f32_ubyte3_e32 v117, v201
	v_cvt_f32_ubyte2_e32 v116, v201
	v_pk_fma_f32 v[104:105], v[112:113], v[114:115], v[104:105]
	v_cvt_f32_ubyte3_e32 v113, v203
	v_cvt_f32_ubyte2_e32 v112, v203
	v_pk_mul_f32 v[116:117], v[116:117], s[16:17] op_sel_hi:[1,0]
	v_pk_mul_f32 v[112:113], v[112:113], s[16:17] op_sel_hi:[1,0]
	v_lshlrev_b32_e32 v114, 16, v151
	v_and_b32_e32 v115, 0xffff0000, v151
	v_pk_mul_f32 v[106:107], v[106:107], v[116:117]
	v_cvt_f32_ubyte1_e32 v117, v196
	v_cvt_f32_ubyte0_e32 v116, v196
	v_pk_fma_f32 v[106:107], v[112:113], v[114:115], v[106:107]
	v_cvt_f32_ubyte1_e32 v113, v198
	v_cvt_f32_ubyte0_e32 v112, v198
	v_pk_mul_f32 v[116:117], v[116:117], s[16:17] op_sel_hi:[1,0]
	v_pk_mul_f32 v[112:113], v[112:113], s[16:17] op_sel_hi:[1,0]
	v_lshlrev_b32_e32 v114, 16, v144
	v_and_b32_e32 v115, 0xffff0000, v144
	v_pk_mul_f32 v[100:101], v[100:101], v[116:117]
	v_cvt_f32_ubyte3_e32 v117, v196
	v_cvt_f32_ubyte2_e32 v116, v196
	v_pk_fma_f32 v[112:113], v[112:113], v[114:115], v[100:101]
	v_cvt_f32_ubyte3_e32 v101, v198
	v_cvt_f32_ubyte2_e32 v100, v198
	v_pk_mul_f32 v[116:117], v[116:117], s[16:17] op_sel_hi:[1,0]
	v_pk_mul_f32 v[100:101], v[100:101], s[16:17] op_sel_hi:[1,0]
	v_lshlrev_b32_e32 v114, 16, v145
	v_and_b32_e32 v115, 0xffff0000, v145
	v_pk_mul_f32 v[102:103], v[102:103], v[116:117]
	v_cvt_f32_ubyte1_e32 v117, v197
	v_cvt_f32_ubyte0_e32 v116, v197
	v_pk_fma_f32 v[114:115], v[100:101], v[114:115], v[102:103]
	v_cvt_f32_ubyte1_e32 v101, v199
	v_cvt_f32_ubyte0_e32 v100, v199
	v_pk_mul_f32 v[116:117], v[116:117], s[16:17] op_sel_hi:[1,0]
	v_pk_mul_f32 v[100:101], v[100:101], s[16:17] op_sel_hi:[1,0]
	v_lshlrev_b32_e32 v102, 16, v146
	v_and_b32_e32 v103, 0xffff0000, v146
	v_pk_mul_f32 v[96:97], v[96:97], v[116:117]
	s_waitcnt lgkmcnt(0)
	s_barrier
	v_pk_fma_f32 v[116:117], v[100:101], v[102:103], v[96:97]
	v_cvt_pk_bf16_f32 v103, v106, v107
	v_cvt_f32_ubyte3_e32 v107, v197
	v_cvt_f32_ubyte2_e32 v106, v197
	v_cvt_pk_bf16_f32 v102, v104, v105
	v_cvt_f32_ubyte3_e32 v105, v199
	v_cvt_f32_ubyte2_e32 v104, v199
	v_pk_mul_f32 v[106:107], v[106:107], s[16:17] op_sel_hi:[1,0]
	v_lshlrev_b32_e32 v96, 16, v147
	v_and_b32_e32 v97, 0xffff0000, v147
	v_pk_mul_f32 v[104:105], v[104:105], s[16:17] op_sel_hi:[1,0]
	v_pk_mul_f32 v[98:99], v[98:99], v[106:107]
	v_cvt_pk_bf16_f32 v100, v108, v109
	v_cvt_pk_bf16_f32 v101, v110, v111
	v_pk_fma_f32 v[104:105], v[104:105], v[96:97], v[98:99]
	v_cvt_pk_bf16_f32 v96, v112, v113
	v_cvt_pk_bf16_f32 v97, v114, v115
	v_cvt_pk_bf16_f32 v98, v116, v117
	v_cvt_pk_bf16_f32 v99, v104, v105
	ds_write_b128 v209, v[100:103]
	ds_write_b128 v209, v[96:99] offset:256
	s_add_u32 s19, s50, s56
	s_waitcnt lgkmcnt(0)
	s_barrier
; #define LAS __attribute__((address_space(3)))
; __device__ __forceinline__ u32x4 pack8(const float (&f)[8]) { u32x4 w; w.x = pk2(f[0], f[1]); w.y = pk2(f[2], f[3]); w.z = pk2(f[4], f[5]); w.w = pk2(f[6], f[7]); return w; }
;     __device__ __forceinline__ void stage512(const u32x4 a, const u32x4 b, unsigned char* g0, size_t ldb, int wr, int wc, int fr, int fq) const {
;         LAS unsigned char* sb = lds + LDS_STG + wr * 8448;
;         *(LAS u32x4*)(sb + fr * 528 + wc * 64 + fq * 16) = a; *(LAS u32x4*)(sb + fr * 528 + 256 + wc * 64 + fq * 16) = b;
;         asm volatile("s_waitcnt lgkmcnt(0)" ::: "memory"); __builtin_amdgcn_s_barrier(); asm volatile("" ::: "memory");
;         const int l = fq * 16 + fr;
; #pragma unroll
;         for (int q = 0; q < 2; ++q) { const int rl = (q * 4 + wc) * 2 + (l >> 5); const u32x4 v = *(const LAS u32x4*)(sb + rl * 528 + (l & 31) * 16); *(u32x4*)(g0 + (size_t)rl * ldb + (l & 31) * 16) = v; }
;         asm volatile("s_waitcnt lgkmcnt(0)" ::: "memory"); __builtin_amdgcn_s_barrier(); asm volatile("" ::: "memory");
;     __device__ __forceinline__ float compute(const Pre& p, f32x4 (&acc)[2][2][4][2], const f32x4 (&cv)[2][2], const pg8::Unit& u, int ai, int m, int wr, int wc, int fr, int fq) const {
;     ...
;             } else if (MODE == EM_MERGE) {
;                 const size_t o = (size_t)row * 1024 + u.pn * 256 + ct;
;                 float b[8]; unpack8(p.b[bj], b);
;                 float w[8];
; #pragma unroll
;                 for (int j = 0; j < 8; ++j) { const unsigned wa = j < 4 ? p.a[bj].x : p.a[bj].y, wc2 = j < 4 ? p.a[bj].z : p.a[bj].w; const int sh = 8 * (j & 3);
;                     const float ga = (float)((wa >> sh) & 255u) * (1.0f / 255.0f), gc = (float)((wc2 >> sh) & 255u) * (1.0f / 255.0f); w[j] = ga * b[j] + gc * v[j]; }
;                 pk[bj] = pack8(w); (void)o;
	s_addc_u32 s21, s51, s57
	ds_read_b128 v[96:99], v210
	ds_read_b128 v[100:103], v210 offset:4224
	s_add_u32 s56, s19, s26
	s_addc_u32 s57, s21, s27
	v_lshl_add_u64 v[104:105], s[56:57], 0, v[164:165]
	v_lshl_add_u64 v[106:107], v[104:105], 0, v[166:167]
	s_waitcnt lgkmcnt(1)
	global_store_dwordx4 v[106:107], v[96:99], off nt
	s_or_b32 s56, s28, 32
	s_ashr_i32 s57, s56, 31
	v_lshl_add_u64 v[96:97], v[104:105], 0, v[168:169]
	s_waitcnt lgkmcnt(0)
	global_store_dwordx4 v[96:97], v[100:103], off nt
	v_cvt_f32_ubyte1_e32 v97, v194
	v_cvt_f32_ubyte0_e32 v96, v194
	v_cvt_f32_ubyte1_e32 v101, v192
	v_cvt_f32_ubyte0_e32 v100, v192
	v_pk_mul_f32 v[100:101], v[100:101], s[16:17] op_sel_hi:[1,0]
	v_pk_mul_f32 v[96:97], v[96:97], s[16:17] op_sel_hi:[1,0]
	v_lshlrev_b32_e32 v98, 16, v140
	v_and_b32_e32 v99, 0xffff0000, v140
	v_pk_mul_f32 v[92:93], v[92:93], v[100:101]
	v_cvt_f32_ubyte3_e32 v101, v192
	v_cvt_f32_ubyte2_e32 v100, v192
	v_pk_fma_f32 v[92:93], v[96:97], v[98:99], v[92:93]
	v_cvt_f32_ubyte3_e32 v97, v194
	v_cvt_f32_ubyte2_e32 v96, v194
	v_pk_mul_f32 v[100:101], v[100:101], s[16:17] op_sel_hi:[1,0]
	v_pk_mul_f32 v[96:97], v[96:97], s[16:17] op_sel_hi:[1,0]
	v_lshlrev_b32_e32 v98, 16, v141
	v_and_b32_e32 v99, 0xffff0000, v141
	v_pk_mul_f32 v[94:95], v[94:95], v[100:101]
	v_cvt_f32_ubyte1_e32 v101, v193
	v_cvt_f32_ubyte0_e32 v100, v193
	v_pk_fma_f32 v[94:95], v[96:97], v[98:99], v[94:95]
	v_cvt_f32_ubyte1_e32 v97, v195
	v_cvt_f32_ubyte0_e32 v96, v195
	v_pk_mul_f32 v[100:101], v[100:101], s[16:17] op_sel_hi:[1,0]
	v_pk_mul_f32 v[96:97], v[96:97], s[16:17] op_sel_hi:[1,0]
	v_lshlrev_b32_e32 v98, 16, v142
	v_and_b32_e32 v99, 0xffff0000, v142
	v_pk_mul_f32 v[88:89], v[88:89], v[100:101]
	v_cvt_f32_ubyte3_e32 v101, v193
	v_cvt_f32_ubyte2_e32 v100, v193
	v_pk_fma_f32 v[88:89], v[96:97], v[98:99], v[88:89]
	v_cvt_f32_ubyte3_e32 v97, v195
	v_cvt_f32_ubyte2_e32 v96, v195
	v_pk_mul_f32 v[100:101], v[100:101], s[16:17] op_sel_hi:[1,0]
	v_pk_mul_f32 v[96:97], v[96:97], s[16:17] op_sel_hi:[1,0]
	v_lshlrev_b32_e32 v98, 16, v143
	v_and_b32_e32 v99, 0xffff0000, v143
	v_pk_mul_f32 v[90:91], v[90:91], v[100:101]
	v_cvt_f32_ubyte1_e32 v101, v188
	v_cvt_f32_ubyte0_e32 v100, v188
	v_pk_fma_f32 v[90:91], v[96:97], v[98:99], v[90:91]
	v_cvt_f32_ubyte1_e32 v97, v190
	v_cvt_f32_ubyte0_e32 v96, v190
	v_pk_mul_f32 v[100:101], v[100:101], s[16:17] op_sel_hi:[1,0]
	v_pk_mul_f32 v[96:97], v[96:97], s[16:17] op_sel_hi:[1,0]
	v_lshlrev_b32_e32 v98, 16, v136
	v_and_b32_e32 v99, 0xffff0000, v136
	v_pk_mul_f32 v[84:85], v[84:85], v[100:101]
	v_cvt_f32_ubyte3_e32 v101, v188
	v_cvt_f32_ubyte2_e32 v100, v188
	v_pk_fma_f32 v[96:97], v[96:97], v[98:99], v[84:85]
	v_cvt_f32_ubyte3_e32 v85, v190
	v_cvt_f32_ubyte2_e32 v84, v190
	v_pk_mul_f32 v[100:101], v[100:101], s[16:17] op_sel_hi:[1,0]
	v_pk_mul_f32 v[84:85], v[84:85], s[16:17] op_sel_hi:[1,0]
	v_lshlrev_b32_e32 v98, 16, v137
	v_and_b32_e32 v99, 0xffff0000, v137
	v_pk_mul_f32 v[86:87], v[86:87], v[100:101]
	v_cvt_f32_ubyte1_e32 v101, v189
	v_cvt_f32_ubyte0_e32 v100, v189
	v_pk_fma_f32 v[98:99], v[84:85], v[98:99], v[86:87]
	v_cvt_f32_ubyte1_e32 v85, v191
	v_cvt_f32_ubyte0_e32 v84, v191
	v_pk_mul_f32 v[100:101], v[100:101], s[16:17] op_sel_hi:[1,0]
	v_pk_mul_f32 v[84:85], v[84:85], s[16:17] op_sel_hi:[1,0]
	v_lshlrev_b32_e32 v86, 16, v138
	v_and_b32_e32 v87, 0xffff0000, v138
	v_pk_mul_f32 v[80:81], v[80:81], v[100:101]
	s_waitcnt lgkmcnt(0)
	s_barrier
	v_pk_fma_f32 v[100:101], v[84:85], v[86:87], v[80:81]
	v_cvt_pk_bf16_f32 v87, v90, v91
	v_cvt_f32_ubyte3_e32 v91, v189
	v_cvt_f32_ubyte2_e32 v90, v189
	v_cvt_pk_bf16_f32 v86, v88, v89
	v_cvt_f32_ubyte3_e32 v89, v191
	v_cvt_f32_ubyte2_e32 v88, v191
	v_pk_mul_f32 v[90:91], v[90:91], s[16:17] op_sel_hi:[1,0]
	v_lshlrev_b32_e32 v80, 16, v139
	v_and_b32_e32 v81, 0xffff0000, v139
	v_pk_mul_f32 v[88:89], v[88:89], s[16:17] op_sel_hi:[1,0]
	v_pk_mul_f32 v[82:83], v[82:83], v[90:91]
	v_cvt_pk_bf16_f32 v84, v92, v93
	v_cvt_pk_bf16_f32 v85, v94, v95
	v_pk_fma_f32 v[88:89], v[88:89], v[80:81], v[82:83]
	v_cvt_pk_bf16_f32 v80, v96, v97
	v_cvt_pk_bf16_f32 v81, v98, v99
	v_cvt_pk_bf16_f32 v82, v100, v101
	v_cvt_pk_bf16_f32 v83, v88, v89
	s_lshl_b64 s[56:57], s[56:57], 11
	ds_write_b128 v209, v[84:87]
	ds_write_b128 v209, v[80:83] offset:256
	s_add_u32 s19, s50, s56
	s_waitcnt lgkmcnt(0)
	s_barrier
; #define LAS __attribute__((address_space(3)))
; __device__ __forceinline__ u32x4 pack8(const float (&f)[8]) { u32x4 w; w.x = pk2(f[0], f[1]); w.y = pk2(f[2], f[3]); w.z = pk2(f[4], f[5]); w.w = pk2(f[6], f[7]); return w; }
;     __device__ __forceinline__ void stage512(const u32x4 a, const u32x4 b, unsigned char* g0, size_t ldb, int wr, int wc, int fr, int fq) const {
;         LAS unsigned char* sb = lds + LDS_STG + wr * 8448;
;         *(LAS u32x4*)(sb + fr * 528 + wc * 64 + fq * 16) = a; *(LAS u32x4*)(sb + fr * 528 + 256 + wc * 64 + fq * 16) = b;
;         asm volatile("s_waitcnt lgkmcnt(0)" ::: "memory"); __builtin_amdgcn_s_barrier(); asm volatile("" ::: "memory");
;         const int l = fq * 16 + fr;
; #pragma unroll
;         for (int q = 0; q < 2; ++q) { const int rl = (q * 4 + wc) * 2 + (l >> 5); const u32x4 v = *(const LAS u32x4*)(sb + rl * 528 + (l & 31) * 16); *(u32x4*)(g0 + (size_t)rl * ldb + (l & 31) * 16) = v; }
;         asm volatile("s_waitcnt lgkmcnt(0)" ::: "memory"); __builtin_amdgcn_s_barrier(); asm volatile("" ::: "memory");
;     __device__ __forceinline__ float compute(const Pre& p, f32x4 (&acc)[2][2][4][2], const f32x4 (&cv)[2][2], const pg8::Unit& u, int ai, int m, int wr, int wc, int fr, int fq) const {
;     ...
;             } else if (MODE == EM_MERGE) {
;                 const size_t o = (size_t)row * 1024 + u.pn * 256 + ct;
;                 float b[8]; unpack8(p.b[bj], b);
;                 float w[8];
; #pragma unroll
;                 for (int j = 0; j < 8; ++j) { const unsigned wa = j < 4 ? p.a[bj].x : p.a[bj].y, wc2 = j < 4 ? p.a[bj].z : p.a[bj].w; const int sh = 8 * (j & 3);
;                     const float ga = (float)((wa >> sh) & 255u) * (1.0f / 255.0f), gc = (float)((wc2 >> sh) & 255u) * (1.0f / 255.0f); w[j] = ga * b[j] + gc * v[j]; }
;                 pk[bj] = pack8(w); (void)o;
	s_addc_u32 s21, s51, s57
	ds_read_b128 v[80:83], v210
	ds_read_b128 v[84:87], v210 offset:4224
	s_add_u32 s56, s19, s26
	s_addc_u32 s57, s21, s27
	v_lshl_add_u64 v[88:89], s[56:57], 0, v[164:165]
	v_lshl_add_u64 v[90:91], v[88:89], 0, v[166:167]
	s_waitcnt lgkmcnt(1)
	global_store_dwordx4 v[90:91], v[80:83], off nt
	s_or_b32 s56, s28, 48
	s_ashr_i32 s57, s56, 31
	v_lshl_add_u64 v[80:81], v[88:89], 0, v[168:169]
	s_waitcnt lgkmcnt(0)
	global_store_dwordx4 v[80:81], v[84:87], off nt
	v_cvt_f32_ubyte1_e32 v81, v186
	v_cvt_f32_ubyte0_e32 v80, v186
	v_cvt_f32_ubyte1_e32 v85, v184
	v_cvt_f32_ubyte0_e32 v84, v184
	v_pk_mul_f32 v[84:85], v[84:85], s[16:17] op_sel_hi:[1,0]
	v_pk_mul_f32 v[80:81], v[80:81], s[16:17] op_sel_hi:[1,0]
	v_lshlrev_b32_e32 v82, 16, v132
	v_and_b32_e32 v83, 0xffff0000, v132
	v_pk_mul_f32 v[76:77], v[76:77], v[84:85]
	v_cvt_f32_ubyte3_e32 v85, v184
	v_cvt_f32_ubyte2_e32 v84, v184
	v_pk_fma_f32 v[76:77], v[80:81], v[82:83], v[76:77]
	v_cvt_f32_ubyte3_e32 v81, v186
	v_cvt_f32_ubyte2_e32 v80, v186
	v_pk_mul_f32 v[84:85], v[84:85], s[16:17] op_sel_hi:[1,0]
	v_pk_mul_f32 v[80:81], v[80:81], s[16:17] op_sel_hi:[1,0]
	v_lshlrev_b32_e32 v82, 16, v133
	v_and_b32_e32 v83, 0xffff0000, v133
	v_pk_mul_f32 v[78:79], v[78:79], v[84:85]
	v_cvt_f32_ubyte1_e32 v85, v185
	v_cvt_f32_ubyte0_e32 v84, v185
	v_pk_fma_f32 v[78:79], v[80:81], v[82:83], v[78:79]
	v_cvt_f32_ubyte1_e32 v81, v187
	v_cvt_f32_ubyte0_e32 v80, v187
	v_pk_mul_f32 v[84:85], v[84:85], s[16:17] op_sel_hi:[1,0]
	v_pk_mul_f32 v[80:81], v[80:81], s[16:17] op_sel_hi:[1,0]
	v_lshlrev_b32_e32 v82, 16, v134
	v_and_b32_e32 v83, 0xffff0000, v134
	v_pk_mul_f32 v[72:73], v[72:73], v[84:85]
	v_cvt_f32_ubyte3_e32 v85, v185
	v_cvt_f32_ubyte2_e32 v84, v185
	v_pk_fma_f32 v[72:73], v[80:81], v[82:83], v[72:73]
	v_cvt_f32_ubyte3_e32 v81, v187
	v_cvt_f32_ubyte2_e32 v80, v187
	v_pk_mul_f32 v[84:85], v[84:85], s[16:17] op_sel_hi:[1,0]
	v_pk_mul_f32 v[80:81], v[80:81], s[16:17] op_sel_hi:[1,0]
	v_lshlrev_b32_e32 v82, 16, v135
	v_and_b32_e32 v83, 0xffff0000, v135
	v_pk_mul_f32 v[74:75], v[74:75], v[84:85]
	v_cvt_f32_ubyte1_e32 v85, v180
	v_cvt_f32_ubyte0_e32 v84, v180
	v_pk_fma_f32 v[74:75], v[80:81], v[82:83], v[74:75]
	v_cvt_f32_ubyte1_e32 v81, v182
	v_cvt_f32_ubyte0_e32 v80, v182
	v_pk_mul_f32 v[84:85], v[84:85], s[16:17] op_sel_hi:[1,0]
	v_pk_mul_f32 v[80:81], v[80:81], s[16:17] op_sel_hi:[1,0]
	v_lshlrev_b32_e32 v82, 16, v128
	v_and_b32_e32 v83, 0xffff0000, v128
	v_pk_mul_f32 v[68:69], v[68:69], v[84:85]
	v_cvt_f32_ubyte3_e32 v85, v180
	v_cvt_f32_ubyte2_e32 v84, v180
	v_pk_fma_f32 v[80:81], v[80:81], v[82:83], v[68:69]
	v_cvt_f32_ubyte3_e32 v69, v182
	v_cvt_f32_ubyte2_e32 v68, v182
	v_pk_mul_f32 v[84:85], v[84:85], s[16:17] op_sel_hi:[1,0]
	v_pk_mul_f32 v[68:69], v[68:69], s[16:17] op_sel_hi:[1,0]
	v_lshlrev_b32_e32 v82, 16, v129
	v_and_b32_e32 v83, 0xffff0000, v129
	v_pk_mul_f32 v[70:71], v[70:71], v[84:85]
	v_cvt_f32_ubyte1_e32 v85, v181
	v_cvt_f32_ubyte0_e32 v84, v181
	v_pk_fma_f32 v[82:83], v[68:69], v[82:83], v[70:71]
	v_cvt_f32_ubyte1_e32 v69, v183
	v_cvt_f32_ubyte0_e32 v68, v183
	v_pk_mul_f32 v[84:85], v[84:85], s[16:17] op_sel_hi:[1,0]
	v_pk_mul_f32 v[68:69], v[68:69], s[16:17] op_sel_hi:[1,0]
	v_lshlrev_b32_e32 v70, 16, v130
	v_and_b32_e32 v71, 0xffff0000, v130
	v_pk_mul_f32 v[64:65], v[64:65], v[84:85]
	s_waitcnt lgkmcnt(0)
	s_barrier
	v_pk_fma_f32 v[84:85], v[68:69], v[70:71], v[64:65]
	v_cvt_pk_bf16_f32 v71, v74, v75
	v_cvt_f32_ubyte3_e32 v75, v181
	v_cvt_f32_ubyte2_e32 v74, v181
	v_cvt_pk_bf16_f32 v70, v72, v73
	v_cvt_f32_ubyte3_e32 v73, v183
	v_cvt_f32_ubyte2_e32 v72, v183
	v_pk_mul_f32 v[74:75], v[74:75], s[16:17] op_sel_hi:[1,0]
	v_lshlrev_b32_e32 v64, 16, v131
	v_and_b32_e32 v65, 0xffff0000, v131
	v_pk_mul_f32 v[72:73], v[72:73], s[16:17] op_sel_hi:[1,0]
	v_pk_mul_f32 v[66:67], v[66:67], v[74:75]
	v_cvt_pk_bf16_f32 v68, v76, v77
	v_cvt_pk_bf16_f32 v69, v78, v79
	v_pk_fma_f32 v[72:73], v[72:73], v[64:65], v[66:67]
	v_cvt_pk_bf16_f32 v64, v80, v81
	v_cvt_pk_bf16_f32 v65, v82, v83
	v_cvt_pk_bf16_f32 v66, v84, v85
	v_cvt_pk_bf16_f32 v67, v72, v73
	s_lshl_b64 s[56:57], s[56:57], 11
	ds_write_b128 v209, v[68:71]
	ds_write_b128 v209, v[64:67] offset:256
	s_add_u32 s19, s50, s56
	s_waitcnt lgkmcnt(0)
	s_barrier
	s_addc_u32 s21, s51, s57
	ds_read_b128 v[64:67], v210
	ds_read_b128 v[68:71], v210 offset:4224
	s_add_u32 s56, s19, s26
	s_addc_u32 s57, s21, s27
	v_lshl_add_u64 v[72:73], s[56:57], 0, v[164:165]
	v_lshl_add_u64 v[74:75], v[72:73], 0, v[166:167]
	s_waitcnt lgkmcnt(1)
	global_store_dwordx4 v[74:75], v[64:67], off nt
	s_nop 1
	v_lshl_add_u64 v[64:65], v[72:73], 0, v[168:169]
	s_waitcnt lgkmcnt(0)
	global_store_dwordx4 v[64:65], v[68:71], off nt
	v_add_u32_e32 v64, 0x80, v178
	v_ashrrev_i32_e32 v65, 31, v64
	v_lshlrev_b64 v[64:65], 11, v[64:65]
	v_lshl_add_u64 v[66:67], s[30:31], 0, v[64:65]
	s_waitcnt lgkmcnt(0)
	s_barrier
; __device__ __forceinline__ u32x4 pack8(const float (&f)[8]) { u32x4 w; w.x = pk2(f[0], f[1]); w.y = pk2(f[2], f[3]); w.z = pk2(f[4], f[5]); w.w = pk2(f[6], f[7]); return w; }
;     __device__ __forceinline__ void load(Pre& p, const pg8::Unit& u, int ai, int m, int wr, int wc, int fr, int fq) const {
;         const int row = u.pm * 256 + ai * 128 + wr * 64 + m * 16 + fr;
;         if (MODE == EM_PROJ || MODE == EM_GATES) p.rs = ((const float*)(ws + WS_RINV0))[row];
;         if (MODE == EM_RES2) p.rs = ((const float*)(ws + WS_SS1))[row];
; #pragma unroll
;         for (int bj = 0; bj < 2; ++bj) {
;             const int ct = bj * 128 + wc * 32 + fq * 8; const size_t o = (size_t)row * 1024 + u.pn * 256 + ct;
;             if (MODE == EM_MERGE) { const unsigned char* g8 = ws + WS_G8 + (size_t)row * 2048 + u.pn * 256 + ct; const u32x2 ga = *(const u32x2*)g8, gc = *(const u32x2*)(g8 + 1024);
;                 p.a[bj] = (u32x4){ga.x, ga.y, gc.x, gc.y}; p.b[bj] = *(const u32x4*)((const bf16_t*)(ws + WS_YHG) + o); }
;             if (MODE == EM_RES1) p.a[bj] = *(const u32x4*)((const bf16_t*)(ws + WS_XB) + o);
;             if (MODE == EM_RES2) { p.b[bj] = *(const u32x4*)((const bf16_t*)(ws + WS_H1B) + o); p.a[bj] = *(const u32x4*)((const bf16_t*)(ws + WS_PE) + o); }
;             if (MODE == EM_GLU && bj == 0) p.a[0] = *(const u32x4*)((const bf16_t*)(ws + WS_ZS) + (size_t)row * 512 + u.pn * 128 + wc * 32 + fq * 8);
;         }
;     }
;     __device__ __forceinline__ float compute(const Pre& p, f32x4 (&acc)[2][2][4][2], const f32x4 (&cv)[2][2], const pg8::Unit& u, int ai, int m, int wr, int wc, int fr, int fq) const {
;     ...
;             } else if (MODE == EM_MERGE) {
;                 const size_t o = (size_t)row * 1024 + u.pn * 256 + ct;
;                 float b[8]; unpack8(p.b[bj], b);
;                 float w[8];
; #pragma unroll
;                 for (int j = 0; j < 8; ++j) { const unsigned wa = j < 4 ? p.a[bj].x : p.a[bj].y, wc2 = j < 4 ? p.a[bj].z : p.a[bj].w; const int sh = 8 * (j & 3);
;                     const float ga = (float)((wa >> sh) & 255u) * (1.0f / 255.0f), gc = (float)((wc2 >> sh) & 255u) * (1.0f / 255.0f); w[j] = ga * b[j] + gc * v[j]; }
;                 pk[bj] = pack8(w); (void)o;
	v_lshl_add_u64 v[66:67], v[66:67], 0, v[162:163]
	global_load_dwordx2 v[120:121], v[66:67], off
	v_lshl_add_u64 v[64:65], s[34:35], 0, v[64:65]
	v_lshl_add_u64 v[64:65], v[64:65], 0, v[160:161]
	global_load_dwordx4 v[112:115], v[64:65], off
	global_load_dwordx2 v[122:123], v[66:67], off offset:1024
	global_load_dwordx2 v[124:125], v[66:67], off offset:1152
	global_load_dwordx2 v[126:127], v[66:67], off offset:128
	global_load_dwordx4 v[116:119], v[64:65], off offset:256
	v_add_u32_e32 v64, 0x90, v178
	v_ashrrev_i32_e32 v65, 31, v64
	v_lshlrev_b64 v[64:65], 11, v[64:65]
	v_lshl_add_u64 v[66:67], s[30:31], 0, v[64:65]
	v_lshl_add_u64 v[66:67], v[66:67], 0, v[162:163]
	v_lshl_add_u64 v[64:65], s[34:35], 0, v[64:65]
	v_lshl_add_u64 v[64:65], v[64:65], 0, v[160:161]
	global_load_dwordx2 v[110:111], v[66:67], off
	global_load_dwordx2 v[108:109], v[66:67], off offset:1024
	global_load_dwordx2 v[104:105], v[66:67], off offset:1152
	global_load_dwordx2 v[106:107], v[66:67], off offset:128
	global_load_dwordx4 v[84:87], v[64:65], off
	global_load_dwordx4 v[80:83], v[64:65], off offset:256
	v_add_u32_e32 v64, 0xa0, v178
	v_ashrrev_i32_e32 v65, 31, v64
	v_lshlrev_b64 v[64:65], 11, v[64:65]
	v_lshl_add_u64 v[66:67], s[30:31], 0, v[64:65]
	v_lshl_add_u64 v[66:67], v[66:67], 0, v[162:163]
	v_lshl_add_u64 v[64:65], s[34:35], 0, v[64:65]
	v_lshl_add_u64 v[64:65], v[64:65], 0, v[160:161]
	global_load_dwordx2 v[102:103], v[66:67], off
	global_load_dwordx2 v[100:101], v[66:67], off offset:1024
	global_load_dwordx2 v[96:97], v[66:67], off offset:1152
	global_load_dwordx2 v[98:99], v[66:67], off offset:128
	global_load_dwordx4 v[76:79], v[64:65], off
	global_load_dwordx4 v[72:75], v[64:65], off offset:256
	v_add_u32_e32 v64, 0xb0, v178
	v_ashrrev_i32_e32 v65, 31, v64
	v_lshlrev_b64 v[64:65], 11, v[64:65]
	v_lshl_add_u64 v[66:67], s[30:31], 0, v[64:65]
	v_lshl_add_u64 v[64:65], s[34:35], 0, v[64:65]
	v_lshl_add_u64 v[66:67], v[66:67], 0, v[162:163]
	v_lshl_add_u64 v[64:65], v[64:65], 0, v[160:161]
	global_load_dwordx2 v[94:95], v[66:67], off
	global_load_dwordx2 v[92:93], v[66:67], off offset:1024
	global_load_dwordx2 v[88:89], v[66:67], off offset:1152
	global_load_dwordx2 v[90:91], v[66:67], off offset:128
	global_load_dwordx4 v[68:71], v[64:65], off
	s_nop 0
	global_load_dwordx4 v[64:67], v[64:65], off offset:256
	s_add_i32 s30, s28, 0x80
	s_ashr_i32 s31, s30, 31
	s_lshl_b64 s[30:31], s[30:31], 11
	s_add_u32 s19, s50, s30
	s_addc_u32 s21, s51, s31
	s_add_u32 s30, s19, s26
	s_addc_u32 s31, s21, s27
	s_waitcnt vmcnt(22)
	v_lshlrev_b32_e32 v130, 16, v112
	s_waitcnt vmcnt(21)
	v_cvt_f32_ubyte1_e32 v133, v122
	v_cvt_f32_ubyte0_e32 v132, v122
	v_cvt_f32_ubyte1_e32 v129, v120
	v_cvt_f32_ubyte0_e32 v128, v120
	v_pk_mul_f32 v[132:133], v[132:133], s[16:17] op_sel_hi:[1,0]
	v_pk_mul_f32 v[128:129], v[128:129], s[16:17] op_sel_hi:[1,0]
	v_and_b32_e32 v131, 0xffff0000, v112
	v_pk_mul_f32 v[60:61], v[60:61], v[132:133]
	v_lshlrev_b32_e32 v112, 16, v113
	v_pk_fma_f32 v[60:61], v[128:129], v[130:131], v[60:61]
	v_cvt_f32_ubyte3_e32 v131, v122
	v_cvt_f32_ubyte2_e32 v130, v122
	v_cvt_f32_ubyte3_e32 v129, v120
	v_cvt_f32_ubyte2_e32 v128, v120
	v_pk_mul_f32 v[130:131], v[130:131], s[16:17] op_sel_hi:[1,0]
	v_pk_mul_f32 v[128:129], v[128:129], s[16:17] op_sel_hi:[1,0]
	v_and_b32_e32 v113, 0xffff0000, v113
	v_pk_mul_f32 v[62:63], v[62:63], v[130:131]
	v_cvt_f32_ubyte1_e32 v131, v123
	v_cvt_f32_ubyte0_e32 v130, v123
	v_pk_fma_f32 v[62:63], v[128:129], v[112:113], v[62:63]
	v_cvt_f32_ubyte1_e32 v113, v121
	v_cvt_f32_ubyte0_e32 v112, v121
	v_pk_mul_f32 v[130:131], v[130:131], s[16:17] op_sel_hi:[1,0]
	v_pk_mul_f32 v[112:113], v[112:113], s[16:17] op_sel_hi:[1,0]
	v_lshlrev_b32_e32 v128, 16, v114
	v_and_b32_e32 v129, 0xffff0000, v114
	v_pk_mul_f32 v[56:57], v[56:57], v[130:131]
	v_cvt_f32_ubyte2_e32 v120, v123
	v_pk_fma_f32 v[56:57], v[112:113], v[128:129], v[56:57]
	v_cvt_f32_ubyte3_e32 v113, v121
	v_cvt_f32_ubyte2_e32 v112, v121
	v_cvt_f32_ubyte3_e32 v121, v123
	v_pk_mul_f32 v[120:121], v[120:121], s[16:17] op_sel_hi:[1,0]
	v_pk_mul_f32 v[112:113], v[112:113], s[16:17] op_sel_hi:[1,0]
	v_lshlrev_b32_e32 v114, 16, v115
	v_and_b32_e32 v115, 0xffff0000, v115
	v_pk_mul_f32 v[58:59], v[58:59], v[120:121]
	s_waitcnt vmcnt(20)
	v_cvt_f32_ubyte1_e32 v121, v124
	v_cvt_f32_ubyte0_e32 v120, v124
	v_pk_fma_f32 v[58:59], v[112:113], v[114:115], v[58:59]
	s_waitcnt vmcnt(19)
	v_cvt_f32_ubyte1_e32 v113, v126
	v_cvt_f32_ubyte0_e32 v112, v126
	v_pk_mul_f32 v[120:121], v[120:121], s[16:17] op_sel_hi:[1,0]
	v_pk_mul_f32 v[112:113], v[112:113], s[16:17] op_sel_hi:[1,0]
	s_waitcnt vmcnt(18)
	v_lshlrev_b32_e32 v114, 16, v116
	v_and_b32_e32 v115, 0xffff0000, v116
	v_pk_mul_f32 v[52:53], v[52:53], v[120:121]
	v_cvt_f32_ubyte2_e32 v116, v124
	v_pk_fma_f32 v[112:113], v[112:113], v[114:115], v[52:53]
	v_lshlrev_b32_e32 v114, 16, v117
	v_and_b32_e32 v115, 0xffff0000, v117
	v_cvt_f32_ubyte3_e32 v117, v124
	v_cvt_f32_ubyte3_e32 v53, v126
	v_cvt_f32_ubyte2_e32 v52, v126
	v_pk_mul_f32 v[116:117], v[116:117], s[16:17] op_sel_hi:[1,0]
	v_pk_mul_f32 v[52:53], v[52:53], s[16:17] op_sel_hi:[1,0]
	v_pk_mul_f32 v[54:55], v[54:55], v[116:117]
	v_cvt_f32_ubyte1_e32 v117, v125
	v_cvt_f32_ubyte0_e32 v116, v125
	v_pk_fma_f32 v[114:115], v[52:53], v[114:115], v[54:55]
	v_cvt_f32_ubyte1_e32 v53, v127
	v_cvt_f32_ubyte0_e32 v52, v127
	v_pk_mul_f32 v[116:117], v[116:117], s[16:17] op_sel_hi:[1,0]
	v_pk_mul_f32 v[52:53], v[52:53], s[16:17] op_sel_hi:[1,0]
	v_lshlrev_b32_e32 v54, 16, v118
	v_and_b32_e32 v55, 0xffff0000, v118
	v_pk_mul_f32 v[48:49], v[48:49], v[116:117]
	s_nop 0
	v_pk_fma_f32 v[116:117], v[52:53], v[54:55], v[48:49]
	v_cvt_pk_bf16_f32 v55, v58, v59
	v_cvt_f32_ubyte3_e32 v59, v125
	v_cvt_f32_ubyte2_e32 v58, v125
	v_cvt_pk_bf16_f32 v54, v56, v57
	v_cvt_f32_ubyte3_e32 v57, v127
	v_cvt_f32_ubyte2_e32 v56, v127
	v_pk_mul_f32 v[58:59], v[58:59], s[16:17] op_sel_hi:[1,0]
	v_lshlrev_b32_e32 v48, 16, v119
	v_and_b32_e32 v49, 0xffff0000, v119
	v_pk_mul_f32 v[56:57], v[56:57], s[16:17] op_sel_hi:[1,0]
	v_pk_mul_f32 v[50:51], v[50:51], v[58:59]
	v_cvt_pk_bf16_f32 v52, v60, v61
	v_cvt_pk_bf16_f32 v53, v62, v63
	v_pk_fma_f32 v[56:57], v[56:57], v[48:49], v[50:51]
	v_cvt_pk_bf16_f32 v48, v112, v113
	v_cvt_pk_bf16_f32 v49, v114, v115
	v_cvt_pk_bf16_f32 v50, v116, v117
	v_cvt_pk_bf16_f32 v51, v56, v57
	ds_write_b128 v209, v[52:55]
	ds_write_b128 v209, v[48:51] offset:256
	s_waitcnt lgkmcnt(0)
	s_barrier
; #define LAS __attribute__((address_space(3)))
; __device__ __forceinline__ u32x4 pack8(const float (&f)[8]) { u32x4 w; w.x = pk2(f[0], f[1]); w.y = pk2(f[2], f[3]); w.z = pk2(f[4], f[5]); w.w = pk2(f[6], f[7]); return w; }
;     __device__ __forceinline__ void stage512(const u32x4 a, const u32x4 b, unsigned char* g0, size_t ldb, int wr, int wc, int fr, int fq) const {
;         LAS unsigned char* sb = lds + LDS_STG + wr * 8448;
;         *(LAS u32x4*)(sb + fr * 528 + wc * 64 + fq * 16) = a; *(LAS u32x4*)(sb + fr * 528 + 256 + wc * 64 + fq * 16) = b;
;         asm volatile("s_waitcnt lgkmcnt(0)" ::: "memory"); __builtin_amdgcn_s_barrier(); asm volatile("" ::: "memory");
;         const int l = fq * 16 + fr;
; #pragma unroll
;         for (int q = 0; q < 2; ++q) { const int rl = (q * 4 + wc) * 2 + (l >> 5); const u32x4 v = *(const LAS u32x4*)(sb + rl * 528 + (l & 31) * 16); *(u32x4*)(g0 + (size_t)rl * ldb + (l & 31) * 16) = v; }
;         asm volatile("s_waitcnt lgkmcnt(0)" ::: "memory"); __builtin_amdgcn_s_barrier(); asm volatile("" ::: "memory");
;     }
;     __device__ __forceinline__ float compute(const Pre& p, f32x4 (&acc)[2][2][4][2], const f32x4 (&cv)[2][2], const pg8::Unit& u, int ai, int m, int wr, int wc, int fr, int fq) const {
;     ...
;             } else if (MODE == EM_MERGE) {
;                 const size_t o = (size_t)row * 1024 + u.pn * 256 + ct;
;                 float b[8]; unpack8(p.b[bj], b);
;                 float w[8];
; #pragma unroll
;                 for (int j = 0; j < 8; ++j) { const unsigned wa = j < 4 ? p.a[bj].x : p.a[bj].y, wc2 = j < 4 ? p.a[bj].z : p.a[bj].w; const int sh = 8 * (j & 3);
;                     const float ga = (float)((wa >> sh) & 255u) * (1.0f / 255.0f), gc = (float)((wc2 >> sh) & 255u) * (1.0f / 255.0f); w[j] = ga * b[j] + gc * v[j]; }
;                 pk[bj] = pack8(w); (void)o;
	ds_read_b128 v[48:51], v210
	ds_read_b128 v[52:55], v210 offset:4224
	v_lshl_add_u64 v[56:57], s[30:31], 0, v[164:165]
	v_lshl_add_u64 v[58:59], v[56:57], 0, v[166:167]
	s_add_i32 s30, s28, 0x90
	s_waitcnt lgkmcnt(1)
	global_store_dwordx4 v[58:59], v[48:51], off nt
	s_ashr_i32 s31, s30, 31
	s_lshl_b64 s[30:31], s[30:31], 11
	v_lshl_add_u64 v[48:49], v[56:57], 0, v[168:169]
	s_waitcnt lgkmcnt(0)
	global_store_dwordx4 v[48:49], v[52:55], off nt
	s_waitcnt vmcnt(19)
	v_cvt_f32_ubyte1_e32 v49, v110
	v_cvt_f32_ubyte0_e32 v48, v110
	s_waitcnt vmcnt(18)
	v_cvt_f32_ubyte1_e32 v53, v108
	v_cvt_f32_ubyte0_e32 v52, v108
	v_pk_mul_f32 v[52:53], v[52:53], s[16:17] op_sel_hi:[1,0]
	v_pk_mul_f32 v[48:49], v[48:49], s[16:17] op_sel_hi:[1,0]
	s_waitcnt vmcnt(15)
	v_lshlrev_b32_e32 v50, 16, v84
	v_and_b32_e32 v51, 0xffff0000, v84
	v_pk_mul_f32 v[44:45], v[44:45], v[52:53]
	v_cvt_f32_ubyte3_e32 v53, v108
	v_cvt_f32_ubyte2_e32 v52, v108
	v_pk_fma_f32 v[44:45], v[48:49], v[50:51], v[44:45]
	v_cvt_f32_ubyte3_e32 v49, v110
	v_cvt_f32_ubyte2_e32 v48, v110
	v_pk_mul_f32 v[52:53], v[52:53], s[16:17] op_sel_hi:[1,0]
	v_pk_mul_f32 v[48:49], v[48:49], s[16:17] op_sel_hi:[1,0]
	v_lshlrev_b32_e32 v50, 16, v85
	v_and_b32_e32 v51, 0xffff0000, v85
	v_pk_mul_f32 v[46:47], v[46:47], v[52:53]
	v_cvt_f32_ubyte1_e32 v53, v109
	v_cvt_f32_ubyte0_e32 v52, v109
	v_pk_fma_f32 v[46:47], v[48:49], v[50:51], v[46:47]
	v_cvt_f32_ubyte1_e32 v49, v111
	v_cvt_f32_ubyte0_e32 v48, v111
	v_pk_mul_f32 v[52:53], v[52:53], s[16:17] op_sel_hi:[1,0]
	v_pk_mul_f32 v[48:49], v[48:49], s[16:17] op_sel_hi:[1,0]
	v_lshlrev_b32_e32 v50, 16, v86
	v_and_b32_e32 v51, 0xffff0000, v86
	v_pk_mul_f32 v[40:41], v[40:41], v[52:53]
	v_cvt_f32_ubyte3_e32 v53, v109
	v_cvt_f32_ubyte2_e32 v52, v109
	v_pk_fma_f32 v[40:41], v[48:49], v[50:51], v[40:41]
	v_cvt_f32_ubyte3_e32 v49, v111
	v_cvt_f32_ubyte2_e32 v48, v111
	v_pk_mul_f32 v[52:53], v[52:53], s[16:17] op_sel_hi:[1,0]
	v_pk_mul_f32 v[48:49], v[48:49], s[16:17] op_sel_hi:[1,0]
	v_lshlrev_b32_e32 v50, 16, v87
	v_and_b32_e32 v51, 0xffff0000, v87
	v_pk_mul_f32 v[42:43], v[42:43], v[52:53]
	v_cvt_f32_ubyte1_e32 v53, v104
	v_cvt_f32_ubyte0_e32 v52, v104
	v_pk_fma_f32 v[42:43], v[48:49], v[50:51], v[42:43]
	v_cvt_f32_ubyte1_e32 v49, v106
	v_cvt_f32_ubyte0_e32 v48, v106
	v_pk_mul_f32 v[52:53], v[52:53], s[16:17] op_sel_hi:[1,0]
	v_pk_mul_f32 v[48:49], v[48:49], s[16:17] op_sel_hi:[1,0]
	s_waitcnt vmcnt(14)
	v_lshlrev_b32_e32 v50, 16, v80
	v_and_b32_e32 v51, 0xffff0000, v80
	v_pk_mul_f32 v[36:37], v[36:37], v[52:53]
	v_cvt_f32_ubyte3_e32 v53, v104
	v_cvt_f32_ubyte2_e32 v52, v104
	v_pk_fma_f32 v[48:49], v[48:49], v[50:51], v[36:37]
	v_cvt_f32_ubyte3_e32 v37, v106
	v_cvt_f32_ubyte2_e32 v36, v106
	v_pk_mul_f32 v[52:53], v[52:53], s[16:17] op_sel_hi:[1,0]
	v_pk_mul_f32 v[36:37], v[36:37], s[16:17] op_sel_hi:[1,0]
	v_lshlrev_b32_e32 v50, 16, v81
	v_and_b32_e32 v51, 0xffff0000, v81
	v_pk_mul_f32 v[38:39], v[38:39], v[52:53]
	v_cvt_f32_ubyte1_e32 v53, v105
	v_cvt_f32_ubyte0_e32 v52, v105
	v_pk_fma_f32 v[50:51], v[36:37], v[50:51], v[38:39]
	v_cvt_f32_ubyte1_e32 v37, v107
	v_cvt_f32_ubyte0_e32 v36, v107
	v_pk_mul_f32 v[52:53], v[52:53], s[16:17] op_sel_hi:[1,0]
	v_pk_mul_f32 v[36:37], v[36:37], s[16:17] op_sel_hi:[1,0]
	v_lshlrev_b32_e32 v38, 16, v82
	v_and_b32_e32 v39, 0xffff0000, v82
	v_pk_mul_f32 v[32:33], v[32:33], v[52:53]
	s_waitcnt lgkmcnt(0)
	s_barrier
	v_pk_fma_f32 v[52:53], v[36:37], v[38:39], v[32:33]
	v_cvt_pk_bf16_f32 v39, v42, v43
	v_cvt_f32_ubyte3_e32 v43, v105
	v_cvt_f32_ubyte2_e32 v42, v105
	v_cvt_pk_bf16_f32 v38, v40, v41
	v_cvt_f32_ubyte3_e32 v41, v107
	v_cvt_f32_ubyte2_e32 v40, v107
	v_pk_mul_f32 v[42:43], v[42:43], s[16:17] op_sel_hi:[1,0]
	v_lshlrev_b32_e32 v32, 16, v83
	v_and_b32_e32 v33, 0xffff0000, v83
	v_pk_mul_f32 v[40:41], v[40:41], s[16:17] op_sel_hi:[1,0]
	v_pk_mul_f32 v[34:35], v[34:35], v[42:43]
	v_cvt_pk_bf16_f32 v36, v44, v45
	v_cvt_pk_bf16_f32 v37, v46, v47
	v_pk_fma_f32 v[40:41], v[40:41], v[32:33], v[34:35]
	v_cvt_pk_bf16_f32 v32, v48, v49
	v_cvt_pk_bf16_f32 v33, v50, v51
	v_cvt_pk_bf16_f32 v34, v52, v53
	v_cvt_pk_bf16_f32 v35, v40, v41
	ds_write_b128 v209, v[36:39]
	ds_write_b128 v209, v[32:35] offset:256
	s_add_u32 s19, s50, s30
	s_waitcnt lgkmcnt(0)
	s_barrier
; #define LAS __attribute__((address_space(3)))
; __device__ __forceinline__ u32x4 pack8(const float (&f)[8]) { u32x4 w; w.x = pk2(f[0], f[1]); w.y = pk2(f[2], f[3]); w.z = pk2(f[4], f[5]); w.w = pk2(f[6], f[7]); return w; }
;     __device__ __forceinline__ void stage512(const u32x4 a, const u32x4 b, unsigned char* g0, size_t ldb, int wr, int wc, int fr, int fq) const {
;         LAS unsigned char* sb = lds + LDS_STG + wr * 8448;
;         *(LAS u32x4*)(sb + fr * 528 + wc * 64 + fq * 16) = a; *(LAS u32x4*)(sb + fr * 528 + 256 + wc * 64 + fq * 16) = b;
;         asm volatile("s_waitcnt lgkmcnt(0)" ::: "memory"); __builtin_amdgcn_s_barrier(); asm volatile("" ::: "memory");
;         const int l = fq * 16 + fr;
; #pragma unroll
;         for (int q = 0; q < 2; ++q) { const int rl = (q * 4 + wc) * 2 + (l >> 5); const u32x4 v = *(const LAS u32x4*)(sb + rl * 528 + (l & 31) * 16); *(u32x4*)(g0 + (size_t)rl * ldb + (l & 31) * 16) = v; }
;         asm volatile("s_waitcnt lgkmcnt(0)" ::: "memory"); __builtin_amdgcn_s_barrier(); asm volatile("" ::: "memory");
;     }
;     __device__ __forceinline__ float compute(const Pre& p, f32x4 (&acc)[2][2][4][2], const f32x4 (&cv)[2][2], const pg8::Unit& u, int ai, int m, int wr, int wc, int fr, int fq) const {
;     ...
;             } else if (MODE == EM_MERGE) {
;                 const size_t o = (size_t)row * 1024 + u.pn * 256 + ct;
;                 float b[8]; unpack8(p.b[bj], b);
;                 float w[8];
; #pragma unroll
;                 for (int j = 0; j < 8; ++j) { const unsigned wa = j < 4 ? p.a[bj].x : p.a[bj].y, wc2 = j < 4 ? p.a[bj].z : p.a[bj].w; const int sh = 8 * (j & 3);
;                     const float ga = (float)((wa >> sh) & 255u) * (1.0f / 255.0f), gc = (float)((wc2 >> sh) & 255u) * (1.0f / 255.0f); w[j] = ga * b[j] + gc * v[j]; }
;                 pk[bj] = pack8(w); (void)o;
	s_addc_u32 s21, s51, s31
	ds_read_b128 v[32:35], v210
	ds_read_b128 v[36:39], v210 offset:4224
	s_add_u32 s30, s19, s26
	s_addc_u32 s31, s21, s27
	v_lshl_add_u64 v[40:41], s[30:31], 0, v[164:165]
	v_lshl_add_u64 v[42:43], v[40:41], 0, v[166:167]
	s_waitcnt lgkmcnt(1)
	global_store_dwordx4 v[42:43], v[32:35], off nt
	s_add_i32 s30, s28, 0xa0
	s_ashr_i32 s31, s30, 31
	v_lshl_add_u64 v[32:33], v[40:41], 0, v[168:169]
	s_waitcnt lgkmcnt(0)
	global_store_dwordx4 v[32:33], v[36:39], off nt
	s_waitcnt vmcnt(15)
	v_cvt_f32_ubyte1_e32 v33, v102
	v_cvt_f32_ubyte0_e32 v32, v102
	s_waitcnt vmcnt(14)
	v_cvt_f32_ubyte1_e32 v37, v100
	v_cvt_f32_ubyte0_e32 v36, v100
	v_pk_mul_f32 v[36:37], v[36:37], s[16:17] op_sel_hi:[1,0]
	v_pk_mul_f32 v[32:33], v[32:33], s[16:17] op_sel_hi:[1,0]
	s_waitcnt vmcnt(11)
	v_lshlrev_b32_e32 v34, 16, v76
	v_and_b32_e32 v35, 0xffff0000, v76
	v_pk_mul_f32 v[28:29], v[28:29], v[36:37]
	v_cvt_f32_ubyte3_e32 v37, v100
	v_cvt_f32_ubyte2_e32 v36, v100
	v_pk_fma_f32 v[28:29], v[32:33], v[34:35], v[28:29]
	v_cvt_f32_ubyte3_e32 v33, v102
	v_cvt_f32_ubyte2_e32 v32, v102
	v_pk_mul_f32 v[36:37], v[36:37], s[16:17] op_sel_hi:[1,0]
	v_pk_mul_f32 v[32:33], v[32:33], s[16:17] op_sel_hi:[1,0]
	v_lshlrev_b32_e32 v34, 16, v77
	v_and_b32_e32 v35, 0xffff0000, v77
	v_pk_mul_f32 v[30:31], v[30:31], v[36:37]
	v_cvt_f32_ubyte1_e32 v37, v101
	v_cvt_f32_ubyte0_e32 v36, v101
	v_pk_fma_f32 v[30:31], v[32:33], v[34:35], v[30:31]
	v_cvt_f32_ubyte1_e32 v33, v103
	v_cvt_f32_ubyte0_e32 v32, v103
	v_pk_mul_f32 v[36:37], v[36:37], s[16:17] op_sel_hi:[1,0]
	v_pk_mul_f32 v[32:33], v[32:33], s[16:17] op_sel_hi:[1,0]
	v_lshlrev_b32_e32 v34, 16, v78
	v_and_b32_e32 v35, 0xffff0000, v78
	v_pk_mul_f32 v[24:25], v[24:25], v[36:37]
	v_cvt_f32_ubyte3_e32 v37, v101
	v_cvt_f32_ubyte2_e32 v36, v101
	v_pk_fma_f32 v[24:25], v[32:33], v[34:35], v[24:25]
	v_cvt_f32_ubyte3_e32 v33, v103
	v_cvt_f32_ubyte2_e32 v32, v103
	v_pk_mul_f32 v[36:37], v[36:37], s[16:17] op_sel_hi:[1,0]
	v_pk_mul_f32 v[32:33], v[32:33], s[16:17] op_sel_hi:[1,0]
	v_lshlrev_b32_e32 v34, 16, v79
	v_and_b32_e32 v35, 0xffff0000, v79
	v_pk_mul_f32 v[26:27], v[26:27], v[36:37]
	v_cvt_f32_ubyte1_e32 v37, v96
	v_cvt_f32_ubyte0_e32 v36, v96
	v_pk_fma_f32 v[26:27], v[32:33], v[34:35], v[26:27]
	v_cvt_f32_ubyte1_e32 v33, v98
	v_cvt_f32_ubyte0_e32 v32, v98
	v_pk_mul_f32 v[36:37], v[36:37], s[16:17] op_sel_hi:[1,0]
	v_pk_mul_f32 v[32:33], v[32:33], s[16:17] op_sel_hi:[1,0]
	s_waitcnt vmcnt(10)
	v_lshlrev_b32_e32 v34, 16, v72
	v_and_b32_e32 v35, 0xffff0000, v72
	v_pk_mul_f32 v[20:21], v[20:21], v[36:37]
	v_cvt_f32_ubyte3_e32 v37, v96
	v_cvt_f32_ubyte2_e32 v36, v96
	v_pk_fma_f32 v[32:33], v[32:33], v[34:35], v[20:21]
	v_cvt_f32_ubyte3_e32 v21, v98
	v_cvt_f32_ubyte2_e32 v20, v98
	v_pk_mul_f32 v[36:37], v[36:37], s[16:17] op_sel_hi:[1,0]
	v_pk_mul_f32 v[20:21], v[20:21], s[16:17] op_sel_hi:[1,0]
	v_lshlrev_b32_e32 v34, 16, v73
	v_and_b32_e32 v35, 0xffff0000, v73
	v_pk_mul_f32 v[22:23], v[22:23], v[36:37]
	v_cvt_f32_ubyte1_e32 v37, v97
	v_cvt_f32_ubyte0_e32 v36, v97
	v_pk_fma_f32 v[34:35], v[20:21], v[34:35], v[22:23]
	v_cvt_f32_ubyte1_e32 v21, v99
	v_cvt_f32_ubyte0_e32 v20, v99
	v_pk_mul_f32 v[36:37], v[36:37], s[16:17] op_sel_hi:[1,0]
	v_pk_mul_f32 v[20:21], v[20:21], s[16:17] op_sel_hi:[1,0]
	v_lshlrev_b32_e32 v22, 16, v74
	v_and_b32_e32 v23, 0xffff0000, v74
	v_pk_mul_f32 v[16:17], v[16:17], v[36:37]
	s_waitcnt lgkmcnt(0)
	s_barrier
	v_pk_fma_f32 v[36:37], v[20:21], v[22:23], v[16:17]
	v_cvt_pk_bf16_f32 v23, v26, v27
	v_cvt_f32_ubyte3_e32 v27, v97
	v_cvt_f32_ubyte2_e32 v26, v97
	v_cvt_pk_bf16_f32 v22, v24, v25
	v_cvt_f32_ubyte3_e32 v25, v99
	v_cvt_f32_ubyte2_e32 v24, v99
	v_pk_mul_f32 v[26:27], v[26:27], s[16:17] op_sel_hi:[1,0]
	v_lshlrev_b32_e32 v16, 16, v75
	v_and_b32_e32 v17, 0xffff0000, v75
	v_pk_mul_f32 v[24:25], v[24:25], s[16:17] op_sel_hi:[1,0]
	v_pk_mul_f32 v[18:19], v[18:19], v[26:27]
	v_cvt_pk_bf16_f32 v20, v28, v29
	v_cvt_pk_bf16_f32 v21, v30, v31
	v_pk_fma_f32 v[24:25], v[24:25], v[16:17], v[18:19]
	v_cvt_pk_bf16_f32 v16, v32, v33
	v_cvt_pk_bf16_f32 v17, v34, v35
	v_cvt_pk_bf16_f32 v18, v36, v37
	v_cvt_pk_bf16_f32 v19, v24, v25
	s_lshl_b64 s[30:31], s[30:31], 11
	ds_write_b128 v209, v[20:23]
	ds_write_b128 v209, v[16:19] offset:256
	s_add_u32 s19, s50, s30
	s_waitcnt lgkmcnt(0)
	s_barrier
; #define LAS __attribute__((address_space(3)))
; __device__ __forceinline__ u32x4 pack8(const float (&f)[8]) { u32x4 w; w.x = pk2(f[0], f[1]); w.y = pk2(f[2], f[3]); w.z = pk2(f[4], f[5]); w.w = pk2(f[6], f[7]); return w; }
;     __device__ __forceinline__ void stage512(const u32x4 a, const u32x4 b, unsigned char* g0, size_t ldb, int wr, int wc, int fr, int fq) const {
;         LAS unsigned char* sb = lds + LDS_STG + wr * 8448;
;         *(LAS u32x4*)(sb + fr * 528 + wc * 64 + fq * 16) = a; *(LAS u32x4*)(sb + fr * 528 + 256 + wc * 64 + fq * 16) = b;
;         asm volatile("s_waitcnt lgkmcnt(0)" ::: "memory"); __builtin_amdgcn_s_barrier(); asm volatile("" ::: "memory");
;         const int l = fq * 16 + fr;
; #pragma unroll
;         for (int q = 0; q < 2; ++q) { const int rl = (q * 4 + wc) * 2 + (l >> 5); const u32x4 v = *(const LAS u32x4*)(sb + rl * 528 + (l & 31) * 16); *(u32x4*)(g0 + (size_t)rl * ldb + (l & 31) * 16) = v; }
;         asm volatile("s_waitcnt lgkmcnt(0)" ::: "memory"); __builtin_amdgcn_s_barrier(); asm volatile("" ::: "memory");
;     }
;     __device__ __forceinline__ float compute(const Pre& p, f32x4 (&acc)[2][2][4][2], const f32x4 (&cv)[2][2], const pg8::Unit& u, int ai, int m, int wr, int wc, int fr, int fq) const {
;     ...
;             } else if (MODE == EM_MERGE) {
;                 const size_t o = (size_t)row * 1024 + u.pn * 256 + ct;
;                 float b[8]; unpack8(p.b[bj], b);
;                 float w[8];
; #pragma unroll
;                 for (int j = 0; j < 8; ++j) { const unsigned wa = j < 4 ? p.a[bj].x : p.a[bj].y, wc2 = j < 4 ? p.a[bj].z : p.a[bj].w; const int sh = 8 * (j & 3);
;                     const float ga = (float)((wa >> sh) & 255u) * (1.0f / 255.0f), gc = (float)((wc2 >> sh) & 255u) * (1.0f / 255.0f); w[j] = ga * b[j] + gc * v[j]; }
;                 pk[bj] = pack8(w); (void)o;
	s_addc_u32 s21, s51, s31
	ds_read_b128 v[16:19], v210
	ds_read_b128 v[20:23], v210 offset:4224
	s_add_u32 s30, s19, s26
	s_addc_u32 s31, s21, s27
	v_lshl_add_u64 v[24:25], s[30:31], 0, v[164:165]
	v_lshl_add_u64 v[26:27], v[24:25], 0, v[166:167]
	s_waitcnt lgkmcnt(1)
	global_store_dwordx4 v[26:27], v[16:19], off nt
	s_addk_i32 s28, 0xb0
	s_ashr_i32 s29, s28, 31
	v_lshl_add_u64 v[16:17], v[24:25], 0, v[168:169]
	s_waitcnt lgkmcnt(0)
	global_store_dwordx4 v[16:17], v[20:23], off nt
	s_waitcnt vmcnt(11)
	v_cvt_f32_ubyte1_e32 v17, v94
	v_cvt_f32_ubyte0_e32 v16, v94
	s_waitcnt vmcnt(10)
	v_cvt_f32_ubyte1_e32 v21, v92
	v_cvt_f32_ubyte0_e32 v20, v92
	v_pk_mul_f32 v[20:21], v[20:21], s[16:17] op_sel_hi:[1,0]
	v_pk_mul_f32 v[16:17], v[16:17], s[16:17] op_sel_hi:[1,0]
	s_waitcnt vmcnt(7)
	v_lshlrev_b32_e32 v18, 16, v68
	v_and_b32_e32 v19, 0xffff0000, v68
	v_pk_mul_f32 v[12:13], v[12:13], v[20:21]
	v_cvt_f32_ubyte3_e32 v21, v92
	v_cvt_f32_ubyte2_e32 v20, v92
	v_pk_fma_f32 v[12:13], v[16:17], v[18:19], v[12:13]
	v_cvt_f32_ubyte3_e32 v17, v94
	v_cvt_f32_ubyte2_e32 v16, v94
	v_pk_mul_f32 v[20:21], v[20:21], s[16:17] op_sel_hi:[1,0]
	v_pk_mul_f32 v[16:17], v[16:17], s[16:17] op_sel_hi:[1,0]
	v_lshlrev_b32_e32 v18, 16, v69
	v_and_b32_e32 v19, 0xffff0000, v69
	v_pk_mul_f32 v[14:15], v[14:15], v[20:21]
	v_cvt_f32_ubyte1_e32 v21, v93
	v_cvt_f32_ubyte0_e32 v20, v93
	v_pk_fma_f32 v[14:15], v[16:17], v[18:19], v[14:15]
	v_cvt_f32_ubyte1_e32 v17, v95
	v_cvt_f32_ubyte0_e32 v16, v95
	v_pk_mul_f32 v[20:21], v[20:21], s[16:17] op_sel_hi:[1,0]
	v_pk_mul_f32 v[16:17], v[16:17], s[16:17] op_sel_hi:[1,0]
	v_lshlrev_b32_e32 v18, 16, v70
	v_and_b32_e32 v19, 0xffff0000, v70
	v_pk_mul_f32 v[8:9], v[8:9], v[20:21]
	v_cvt_f32_ubyte3_e32 v21, v93
	v_cvt_f32_ubyte2_e32 v20, v93
	v_pk_fma_f32 v[8:9], v[16:17], v[18:19], v[8:9]
	v_cvt_f32_ubyte3_e32 v17, v95
	v_cvt_f32_ubyte2_e32 v16, v95
	v_pk_mul_f32 v[20:21], v[20:21], s[16:17] op_sel_hi:[1,0]
	v_pk_mul_f32 v[16:17], v[16:17], s[16:17] op_sel_hi:[1,0]
	v_lshlrev_b32_e32 v18, 16, v71
	v_and_b32_e32 v19, 0xffff0000, v71
	v_pk_mul_f32 v[10:11], v[10:11], v[20:21]
	v_cvt_f32_ubyte1_e32 v21, v88
	v_cvt_f32_ubyte0_e32 v20, v88
	v_pk_fma_f32 v[10:11], v[16:17], v[18:19], v[10:11]
	v_cvt_f32_ubyte1_e32 v17, v90
	v_cvt_f32_ubyte0_e32 v16, v90
	v_pk_mul_f32 v[20:21], v[20:21], s[16:17] op_sel_hi:[1,0]
	v_pk_mul_f32 v[16:17], v[16:17], s[16:17] op_sel_hi:[1,0]
	s_waitcnt vmcnt(6)
	v_lshlrev_b32_e32 v18, 16, v64
	v_and_b32_e32 v19, 0xffff0000, v64
	v_pk_mul_f32 v[4:5], v[4:5], v[20:21]
	v_cvt_f32_ubyte3_e32 v21, v88
	v_cvt_f32_ubyte2_e32 v20, v88
	v_pk_fma_f32 v[16:17], v[16:17], v[18:19], v[4:5]
	v_cvt_f32_ubyte3_e32 v5, v90
	v_cvt_f32_ubyte2_e32 v4, v90
	v_pk_mul_f32 v[20:21], v[20:21], s[16:17] op_sel_hi:[1,0]
	v_pk_mul_f32 v[4:5], v[4:5], s[16:17] op_sel_hi:[1,0]
	v_lshlrev_b32_e32 v18, 16, v65
	v_and_b32_e32 v19, 0xffff0000, v65
	v_pk_mul_f32 v[6:7], v[6:7], v[20:21]
	v_cvt_f32_ubyte1_e32 v21, v89
	v_cvt_f32_ubyte0_e32 v20, v89
	v_pk_fma_f32 v[18:19], v[4:5], v[18:19], v[6:7]
	v_cvt_f32_ubyte1_e32 v5, v91
	v_cvt_f32_ubyte0_e32 v4, v91
	v_pk_mul_f32 v[20:21], v[20:21], s[16:17] op_sel_hi:[1,0]
	v_pk_mul_f32 v[4:5], v[4:5], s[16:17] op_sel_hi:[1,0]
	v_lshlrev_b32_e32 v6, 16, v66
	v_and_b32_e32 v7, 0xffff0000, v66
	v_pk_mul_f32 v[0:1], v[0:1], v[20:21]
	s_waitcnt lgkmcnt(0)
	s_barrier
	v_pk_fma_f32 v[20:21], v[4:5], v[6:7], v[0:1]
	v_cvt_pk_bf16_f32 v7, v10, v11
	v_cvt_f32_ubyte3_e32 v11, v89
	v_cvt_f32_ubyte2_e32 v10, v89
	v_cvt_pk_bf16_f32 v6, v8, v9
	v_cvt_f32_ubyte3_e32 v9, v91
	v_cvt_f32_ubyte2_e32 v8, v91
	v_pk_mul_f32 v[10:11], v[10:11], s[16:17] op_sel_hi:[1,0]
	v_lshlrev_b32_e32 v0, 16, v67
	v_and_b32_e32 v1, 0xffff0000, v67
	v_pk_mul_f32 v[8:9], v[8:9], s[16:17] op_sel_hi:[1,0]
	v_pk_mul_f32 v[2:3], v[2:3], v[10:11]
	v_cvt_pk_bf16_f32 v4, v12, v13
	v_cvt_pk_bf16_f32 v5, v14, v15
	v_pk_fma_f32 v[8:9], v[8:9], v[0:1], v[2:3]
	v_cvt_pk_bf16_f32 v0, v16, v17
	v_cvt_pk_bf16_f32 v1, v18, v19
	v_cvt_pk_bf16_f32 v2, v20, v21
	v_cvt_pk_bf16_f32 v3, v8, v9
	s_lshl_b64 s[28:29], s[28:29], 11
	ds_write_b128 v209, v[4:7]
	ds_write_b128 v209, v[0:3] offset:256
	s_add_u32 s19, s50, s28
	s_waitcnt lgkmcnt(0)
	s_barrier
	s_addc_u32 s21, s51, s29
	ds_read_b128 v[0:3], v210
	ds_read_b128 v[4:7], v210 offset:4224
	s_add_u32 s26, s19, s26
	s_addc_u32 s27, s21, s27
	v_lshl_add_u64 v[8:9], s[26:27], 0, v[164:165]
	v_lshl_add_u64 v[10:11], v[8:9], 0, v[166:167]
	s_waitcnt lgkmcnt(1)
	global_store_dwordx4 v[10:11], v[0:3], off nt
	s_andn2_b64 vcc, exec, s[4:5]
	s_mov_b64 s[4:5], -1
	v_lshl_add_u64 v[0:1], v[8:9], 0, v[168:169]
	s_waitcnt lgkmcnt(0)
	global_store_dwordx4 v[0:1], v[4:7], off nt
	s_waitcnt lgkmcnt(0)
	s_barrier
	s_cbranch_vccnz .LBB0_1138
	s_andn2_b64 vcc, exec, s[10:11]
	s_cbranch_vccnz .LBB0_1137
	s_barrier
	s_branch .LBB0_1137

; __device__ __forceinline__ u32x4 pack8(const float (&f)[8]) { u32x4 w; w.x = pk2(f[0], f[1]); w.y = pk2(f[2], f[3]); w.z = pk2(f[4], f[5]); w.w = pk2(f[6], f[7]); return w; }
;     __device__ __forceinline__ void load(Pre& p, const pg8::Unit& u, int ai, int m, int wr, int wc, int fr, int fq) const {
;         const int row = u.pm * 256 + ai * 128 + wr * 64 + m * 16 + fr;
;         if (MODE == EM_PROJ || MODE == EM_GATES) p.rs = ((const float*)(ws + WS_RINV0))[row];
;         if (MODE == EM_RES2) p.rs = ((const float*)(ws + WS_SS1))[row];
; #pragma unroll
;         for (int bj = 0; bj < 2; ++bj) {
;             const int ct = bj * 128 + wc * 32 + fq * 8; const size_t o = (size_t)row * 1024 + u.pn * 256 + ct;
;             if (MODE == EM_MERGE) { const unsigned char* g8 = ws + WS_G8 + (size_t)row * 2048 + u.pn * 256 + ct; const u32x2 ga = *(const u32x2*)g8, gc = *(const u32x2*)(g8 + 1024);
;                 p.a[bj] = (u32x4){ga.x, ga.y, gc.x, gc.y}; p.b[bj] = *(const u32x4*)((const bf16_t*)(ws + WS_YHG) + o); }
;             if (MODE == EM_RES1) p.a[bj] = *(const u32x4*)((const bf16_t*)(ws + WS_XB) + o);
;             if (MODE == EM_RES2) { p.b[bj] = *(const u32x4*)((const bf16_t*)(ws + WS_H1B) + o); p.a[bj] = *(const u32x4*)((const bf16_t*)(ws + WS_PE) + o); }
;             if (MODE == EM_GLU && bj == 0) p.a[0] = *(const u32x4*)((const bf16_t*)(ws + WS_ZS) + (size_t)row * 512 + u.pn * 128 + wc * 32 + fq * 8);
;         }
;     }
;     __device__ __forceinline__ float compute(const Pre& p, f32x4 (&acc)[2][2][4][2], const f32x4 (&cv)[2][2], const pg8::Unit& u, int ai, int m, int wr, int wc, int fr, int fq) const {
;     ...
;             } else if (MODE == EM_RES1) {
;                 const size_t o = (size_t)row * 1024 + u.pn * 256 + ct;
;                 float w[8], xr[8]; unpack8(p.a[bj], xr);
; #pragma unroll
;                 for (int j = 0; j < 8; ++j) { w[j] = v[j] + xr[j]; ssq += w[j] * w[j]; }
;                 pk[bj] = pack8(w); (void)o;
.LBB0_1254:
	s_lshl_b32 s23, s30, 8
	s_add_i32 s34, s23, s3
	s_lshl_b32 s30, s31, 8
	v_or_b32_e32 v170, s34, v176
	s_ashr_i32 s31, s30, 31
	s_lshl_b64 s[30:31], s[30:31], 1
	v_ashrrev_i32_e32 v171, 31, v170
	v_lshl_add_u64 v[172:173], v[160:161], 0, s[30:31]
	v_lshlrev_b64 v[128:129], 11, v[170:171]
	v_lshl_add_u64 v[130:131], v[172:173], 0, v[128:129]
	v_lshl_add_u64 v[174:175], v[158:159], 0, s[30:31]
	global_load_dwordx4 v[184:187], v[130:131], off
	v_lshl_add_u64 v[128:129], v[174:175], 0, v[128:129]
	v_add_co_u32_e32 v128, vcc, 0x3400000, v128
	v_or_b32_e32 v132, 48, v170
	s_nop 0
	v_addc_co_u32_e32 v129, vcc, 0, v129, vcc
	global_load_dwordx4 v[188:191], v[128:129], off offset:256
	v_or_b32_e32 v128, 16, v170
	v_ashrrev_i32_e32 v129, 31, v128
	v_lshlrev_b64 v[128:129], 11, v[128:129]
	v_lshl_add_u64 v[134:135], v[172:173], 0, v[128:129]
	v_lshl_add_u64 v[128:129], v[174:175], 0, v[128:129]
	v_add_co_u32_e32 v128, vcc, 0x3400000, v128
	v_or_b32_e32 v130, 32, v170
	s_nop 0
	v_addc_co_u32_e32 v129, vcc, 0, v129, vcc
	global_load_dwordx4 v[192:195], v[134:135], off
	global_load_dwordx4 v[196:199], v[128:129], off offset:256
	v_ashrrev_i32_e32 v131, 31, v130
	v_lshlrev_b64 v[130:131], 11, v[130:131]
	v_lshl_add_u64 v[136:137], v[172:173], 0, v[130:131]
	v_lshl_add_u64 v[130:131], v[174:175], 0, v[130:131]
	v_add_co_u32_e32 v130, vcc, 0x3400000, v130
	v_ashrrev_i32_e32 v133, 31, v132
	s_nop 0
	v_addc_co_u32_e32 v131, vcc, 0, v131, vcc
	global_load_dwordx4 v[140:143], v[136:137], off
	s_nop 0
	global_load_dwordx4 v[136:139], v[130:131], off offset:256
	v_lshlrev_b64 v[132:133], 11, v[132:133]
	v_lshl_add_u64 v[200:201], v[172:173], 0, v[132:133]
	v_lshl_add_u64 v[132:133], v[174:175], 0, v[132:133]
	v_add_co_u32_e32 v128, vcc, 0x3400000, v132
	s_ashr_i32 s35, s34, 31
	s_nop 0
	v_addc_co_u32_e32 v129, vcc, 0, v133, vcc
	global_load_dwordx4 v[132:135], v[200:201], off
	s_nop 0
	global_load_dwordx4 v[128:131], v[128:129], off offset:256
	s_lshl_b64 s[36:37], s[34:35], 11
	s_add_u32 s23, s58, s36
	s_addc_u32 s25, s59, s37
	s_add_u32 s36, s23, s30
	s_addc_u32 s37, s25, s31
	s_waitcnt vmcnt(0)
	v_lshlrev_b32_e32 v200, 16, v184
	v_and_b32_e32 v201, 0xffff0000, v184
	v_lshlrev_b32_e32 v184, 16, v185
	v_and_b32_e32 v185, 0xffff0000, v185
	v_pk_add_f32 v[124:125], v[124:125], v[200:201]
	v_lshlrev_b32_e32 v202, 16, v186
	v_and_b32_e32 v203, 0xffff0000, v186
	v_pk_add_f32 v[126:127], v[126:127], v[184:185]
	v_pk_mul_f32 v[200:201], v[124:125], v[124:125]
	v_pk_add_f32 v[184:185], v[120:121], v[202:203]
	v_pk_mul_f32 v[202:203], v[126:127], v[126:127]
	v_cvt_pk_bf16_f32 v120, v124, v125
	v_lshlrev_b32_e32 v124, 16, v188
	v_and_b32_e32 v125, 0xffff0000, v188
	v_add_f32_e32 v188, v200, v201
	v_add_f32_e32 v188, v202, v188
	v_lshlrev_b32_e32 v186, 16, v187
	v_and_b32_e32 v187, 0xffff0000, v187
	v_pk_mul_f32 v[204:205], v[184:185], v[184:185]
	v_add_f32_e32 v188, v203, v188
	v_pk_add_f32 v[186:187], v[122:123], v[186:187]
	v_add_f32_e32 v188, v204, v188
	v_pk_mul_f32 v[206:207], v[186:187], v[186:187]
	v_add_f32_e32 v188, v205, v188
	v_cvt_pk_bf16_f32 v122, v184, v185
	v_lshlrev_b32_e32 v184, 16, v190
	v_and_b32_e32 v185, 0xffff0000, v190
	v_pk_add_f32 v[116:117], v[116:117], v[124:125]
	v_add_f32_e32 v188, v206, v188
	v_cvt_pk_bf16_f32 v121, v126, v127
	v_lshlrev_b32_e32 v126, 16, v189
	v_and_b32_e32 v127, 0xffff0000, v189
	v_pk_add_f32 v[124:125], v[112:113], v[184:185]
	v_pk_mul_f32 v[112:113], v[116:117], v[116:117]
	v_add_f32_e32 v188, v207, v188
	v_cvt_pk_bf16_f32 v123, v186, v187
	v_lshlrev_b32_e32 v186, 16, v191
	v_and_b32_e32 v187, 0xffff0000, v191
	v_pk_add_f32 v[118:119], v[118:119], v[126:127]
	v_add_f32_e32 v112, v112, v188
	v_pk_add_f32 v[126:127], v[114:115], v[186:187]
	v_pk_mul_f32 v[114:115], v[118:119], v[118:119]
	v_add_f32_e32 v112, v113, v112
	v_add_f32_e32 v112, v114, v112
	v_pk_mul_f32 v[184:185], v[124:125], v[124:125]
	v_add_f32_e32 v112, v115, v112
	v_add_f32_e32 v112, v184, v112
	v_pk_mul_f32 v[186:187], v[126:127], v[126:127]
	v_add_f32_e32 v112, v185, v112
	v_add_f32_e32 v112, v186, v112
	v_add_f32_e32 v184, v187, v112
	v_cvt_pk_bf16_f32 v112, v116, v117
	v_cvt_pk_bf16_f32 v113, v118, v119
	v_cvt_pk_bf16_f32 v114, v124, v125
	v_cvt_pk_bf16_f32 v115, v126, v127
	ds_write_b128 v181, v[120:123]
	ds_write_b128 v181, v[112:115] offset:256
	s_waitcnt lgkmcnt(0)
	s_barrier
; #define LAS __attribute__((address_space(3)))
; __device__ __forceinline__ u32x4 pack8(const float (&f)[8]) { u32x4 w; w.x = pk2(f[0], f[1]); w.y = pk2(f[2], f[3]); w.z = pk2(f[4], f[5]); w.w = pk2(f[6], f[7]); return w; }
;     __device__ __forceinline__ void stage512(const u32x4 a, const u32x4 b, unsigned char* g0, size_t ldb, int wr, int wc, int fr, int fq) const {
;         LAS unsigned char* sb = lds + LDS_STG + wr * 8448;
;         *(LAS u32x4*)(sb + fr * 528 + wc * 64 + fq * 16) = a; *(LAS u32x4*)(sb + fr * 528 + 256 + wc * 64 + fq * 16) = b;
;         asm volatile("s_waitcnt lgkmcnt(0)" ::: "memory"); __builtin_amdgcn_s_barrier(); asm volatile("" ::: "memory");
;         const int l = fq * 16 + fr;
; #pragma unroll
;         for (int q = 0; q < 2; ++q) { const int rl = (q * 4 + wc) * 2 + (l >> 5); const u32x4 v = *(const LAS u32x4*)(sb + rl * 528 + (l & 31) * 16); *(u32x4*)(g0 + (size_t)rl * ldb + (l & 31) * 16) = v; }
;         asm volatile("s_waitcnt lgkmcnt(0)" ::: "memory"); __builtin_amdgcn_s_barrier(); asm volatile("" ::: "memory");
;     }
;     __device__ __forceinline__ float compute(const Pre& p, f32x4 (&acc)[2][2][4][2], const f32x4 (&cv)[2][2], const pg8::Unit& u, int ai, int m, int wr, int wc, int fr, int fq) const {
;     ...
;             } else if (MODE == EM_RES1) {
;                 const size_t o = (size_t)row * 1024 + u.pn * 256 + ct;
;                 float w[8], xr[8]; unpack8(p.a[bj], xr);
; #pragma unroll
;                 for (int j = 0; j < 8; ++j) { w[j] = v[j] + xr[j]; ssq += w[j] * w[j]; }
;                 pk[bj] = pack8(w); (void)o;
	ds_read_b128 v[112:115], v182
	ds_read_b128 v[116:119], v182 offset:4224
	v_lshl_add_u64 v[120:121], s[36:37], 0, v[152:153]
	v_lshl_add_u64 v[122:123], v[120:121], 0, v[154:155]
	s_or_b32 s36, s34, 16
	s_waitcnt lgkmcnt(1)
	global_store_dwordx4 v[122:123], v[112:115], off nt
	s_ashr_i32 s37, s36, 31
	s_lshl_b64 s[36:37], s[36:37], 11
	v_and_b32_e32 v115, 64, v183
	v_xor_b32_e32 v114, 16, v183
	v_add_u32_e32 v115, 64, v115
	v_cmp_lt_i32_e32 vcc, v114, v115
	v_lshl_add_u64 v[112:113], v[120:121], 0, v[156:157]
	s_waitcnt lgkmcnt(0)
	global_store_dwordx4 v[112:113], v[116:119], off nt
	v_cndmask_b32_e32 v114, v183, v114, vcc
	v_lshlrev_b32_e32 v114, 2, v114
	ds_bpermute_b32 v120, v114, v184
	v_lshlrev_b32_e32 v116, 16, v192
	v_and_b32_e32 v117, 0xffff0000, v192
	v_pk_add_f32 v[108:109], v[108:109], v[116:117]
	v_lshlrev_b32_e32 v118, 16, v193
	v_and_b32_e32 v119, 0xffff0000, v193
	v_pk_mul_f32 v[116:117], v[108:109], v[108:109]
	v_pk_add_f32 v[110:111], v[110:111], v[118:119]
	s_waitcnt lgkmcnt(0)
	v_add_f32_e32 v112, v184, v120
	v_pk_mul_f32 v[118:119], v[110:111], v[110:111]
	v_lshlrev_b32_e32 v120, 16, v194
	v_and_b32_e32 v121, 0xffff0000, v194
	v_add_f32_e32 v116, v116, v117
	v_pk_add_f32 v[120:121], v[104:105], v[120:121]
	v_add_f32_e32 v116, v118, v116
	v_pk_mul_f32 v[122:123], v[120:121], v[120:121]
	v_lshlrev_b32_e32 v104, 16, v195
	v_and_b32_e32 v105, 0xffff0000, v195
	v_add_f32_e32 v116, v119, v116
	v_pk_add_f32 v[124:125], v[106:107], v[104:105]
	v_add_f32_e32 v116, v122, v116
	v_pk_mul_f32 v[126:127], v[124:125], v[124:125]
	v_cvt_pk_bf16_f32 v104, v108, v109
	v_lshlrev_b32_e32 v108, 16, v196
	v_and_b32_e32 v109, 0xffff0000, v196
	v_add_f32_e32 v116, v123, v116
	v_pk_add_f32 v[100:101], v[100:101], v[108:109]
	v_add_f32_e32 v116, v126, v116
	v_cvt_pk_bf16_f32 v105, v110, v111
	v_pk_mul_f32 v[108:109], v[100:101], v[100:101]
	v_lshlrev_b32_e32 v110, 16, v197
	v_and_b32_e32 v111, 0xffff0000, v197
	v_add_f32_e32 v116, v127, v116
	v_pk_add_f32 v[102:103], v[102:103], v[110:111]
	v_add_f32_e32 v108, v108, v116
	v_cvt_pk_bf16_f32 v106, v120, v121
	v_pk_mul_f32 v[110:111], v[102:103], v[102:103]
	v_lshlrev_b32_e32 v120, 16, v198
	v_and_b32_e32 v121, 0xffff0000, v198
	v_add_f32_e32 v108, v109, v108
	v_pk_add_f32 v[120:121], v[96:97], v[120:121]
	v_add_f32_e32 v108, v110, v108
	v_cvt_pk_bf16_f32 v107, v124, v125
	v_pk_mul_f32 v[96:97], v[120:121], v[120:121]
	v_lshlrev_b32_e32 v124, 16, v199
	v_and_b32_e32 v125, 0xffff0000, v199
	v_add_f32_e32 v108, v111, v108
	v_pk_add_f32 v[124:125], v[98:99], v[124:125]
	v_add_f32_e32 v96, v96, v108
	v_pk_mul_f32 v[98:99], v[124:125], v[124:125]
	v_add_f32_e32 v96, v97, v96
	v_add_f32_e32 v96, v98, v96
	s_waitcnt lgkmcnt(0)
	s_barrier
	v_add_f32_e32 v116, v99, v96
	v_cvt_pk_bf16_f32 v96, v100, v101
	v_cvt_pk_bf16_f32 v97, v102, v103
	v_cvt_pk_bf16_f32 v98, v120, v121
	v_cvt_pk_bf16_f32 v99, v124, v125
	ds_write_b128 v181, v[104:107]
	ds_write_b128 v181, v[96:99] offset:256
	s_add_u32 s23, s58, s36
	s_waitcnt lgkmcnt(0)
	s_barrier
	s_addc_u32 s25, s59, s37
	ds_read_b128 v[96:99], v182
	ds_read_b128 v[100:103], v182 offset:4224
	s_add_u32 s36, s23, s30
	s_addc_u32 s37, s25, s31
	v_lshl_add_u64 v[104:105], s[36:37], 0, v[152:153]
	v_lshl_add_u64 v[106:107], v[104:105], 0, v[154:155]
	s_waitcnt lgkmcnt(1)
	global_store_dwordx4 v[106:107], v[96:99], off nt
	s_or_b32 s36, s34, 32
	s_ashr_i32 s37, s36, 31
	v_lshl_add_u64 v[96:97], v[104:105], 0, v[156:157]
	s_waitcnt lgkmcnt(0)
	global_store_dwordx4 v[96:97], v[100:103], off nt
	v_lshlrev_b32_e32 v96, 16, v140
	v_and_b32_e32 v97, 0xffff0000, v140
	v_lshlrev_b32_e32 v100, 16, v142
	v_and_b32_e32 v101, 0xffff0000, v142
	v_pk_add_f32 v[100:101], v[88:89], v[100:101]
	v_lshlrev_b32_e32 v88, 16, v143
	v_and_b32_e32 v89, 0xffff0000, v143
	v_pk_add_f32 v[92:93], v[92:93], v[96:97]
	v_lshlrev_b32_e32 v98, 16, v141
	v_and_b32_e32 v99, 0xffff0000, v141
	v_pk_mul_f32 v[102:103], v[100:101], v[100:101]
	v_pk_add_f32 v[104:105], v[90:91], v[88:89]
	v_cvt_pk_bf16_f32 v90, v100, v101
	v_lshlrev_b32_e32 v100, 16, v138
	v_and_b32_e32 v101, 0xffff0000, v138
	v_pk_mul_f32 v[96:97], v[92:93], v[92:93]
	v_pk_add_f32 v[94:95], v[94:95], v[98:99]
	v_pk_add_f32 v[100:101], v[80:81], v[100:101]
	v_lshlrev_b32_e32 v80, 16, v139
	v_and_b32_e32 v81, 0xffff0000, v139
	v_pk_mul_f32 v[98:99], v[94:95], v[94:95]
	v_pk_add_f32 v[108:109], v[82:83], v[80:81]
	v_add_f32_e32 v80, v96, v97
	v_add_f32_e32 v80, v98, v80
	v_add_f32_e32 v80, v99, v80
	v_add_f32_e32 v80, v102, v80
	v_pk_mul_f32 v[106:107], v[104:105], v[104:105]
	v_cvt_pk_bf16_f32 v88, v92, v93
	v_cvt_pk_bf16_f32 v89, v94, v95
	v_lshlrev_b32_e32 v92, 16, v136
	v_and_b32_e32 v93, 0xffff0000, v136
	v_lshlrev_b32_e32 v94, 16, v137
	v_and_b32_e32 v95, 0xffff0000, v137
	v_add_f32_e32 v80, v103, v80
	v_cvt_pk_bf16_f32 v91, v104, v105
	v_pk_add_f32 v[84:85], v[84:85], v[92:93]
	v_pk_add_f32 v[86:87], v[86:87], v[94:95]
	v_add_f32_e32 v80, v106, v80
	s_waitcnt lgkmcnt(0)
	s_barrier
	v_add_f32_e32 v102, v107, v80
	v_cvt_pk_bf16_f32 v80, v84, v85
	v_cvt_pk_bf16_f32 v81, v86, v87
	v_cvt_pk_bf16_f32 v82, v100, v101
	v_cvt_pk_bf16_f32 v83, v108, v109
	s_lshl_b64 s[36:37], s[36:37], 11
	ds_write_b128 v181, v[88:91]
	ds_write_b128 v181, v[80:83] offset:256
	s_add_u32 s23, s58, s36
	s_waitcnt lgkmcnt(0)
	s_barrier
; #define LAS __attribute__((address_space(3)))
; __device__ __forceinline__ u32x4 pack8(const float (&f)[8]) { u32x4 w; w.x = pk2(f[0], f[1]); w.y = pk2(f[2], f[3]); w.z = pk2(f[4], f[5]); w.w = pk2(f[6], f[7]); return w; }
;     __device__ __forceinline__ void stage512(const u32x4 a, const u32x4 b, unsigned char* g0, size_t ldb, int wr, int wc, int fr, int fq) const {
;         LAS unsigned char* sb = lds + LDS_STG + wr * 8448;
;         *(LAS u32x4*)(sb + fr * 528 + wc * 64 + fq * 16) = a; *(LAS u32x4*)(sb + fr * 528 + 256 + wc * 64 + fq * 16) = b;
;         asm volatile("s_waitcnt lgkmcnt(0)" ::: "memory"); __builtin_amdgcn_s_barrier(); asm volatile("" ::: "memory");
;         const int l = fq * 16 + fr;
; #pragma unroll
;         for (int q = 0; q < 2; ++q) { const int rl = (q * 4 + wc) * 2 + (l >> 5); const u32x4 v = *(const LAS u32x4*)(sb + rl * 528 + (l & 31) * 16); *(u32x4*)(g0 + (size_t)rl * ldb + (l & 31) * 16) = v; }
;         asm volatile("s_waitcnt lgkmcnt(0)" ::: "memory"); __builtin_amdgcn_s_barrier(); asm volatile("" ::: "memory");
;     }
;     __device__ __forceinline__ float compute(const Pre& p, f32x4 (&acc)[2][2][4][2], const f32x4 (&cv)[2][2], const pg8::Unit& u, int ai, int m, int wr, int wc, int fr, int fq) const {
;     ...
;             } else if (MODE == EM_RES1) {
;                 const size_t o = (size_t)row * 1024 + u.pn * 256 + ct;
;                 float w[8], xr[8]; unpack8(p.a[bj], xr);
; #pragma unroll
;                 for (int j = 0; j < 8; ++j) { w[j] = v[j] + xr[j]; ssq += w[j] * w[j]; }
;                 pk[bj] = pack8(w); (void)o;
	s_addc_u32 s25, s59, s37
	ds_read_b128 v[80:83], v182
	v_pk_mul_f32 v[92:93], v[84:85], v[84:85]
	v_pk_mul_f32 v[94:95], v[86:87], v[86:87]
	s_add_u32 s36, s23, s30
	ds_read_b128 v[84:87], v182 offset:4224
	s_addc_u32 s37, s25, s31
	v_lshl_add_u64 v[88:89], s[36:37], 0, v[152:153]
	v_lshl_add_u64 v[90:91], v[88:89], 0, v[154:155]
	s_waitcnt lgkmcnt(1)
	global_store_dwordx4 v[90:91], v[80:83], off nt
	s_or_b32 s36, s34, 48
	v_pk_mul_f32 v[104:105], v[100:101], v[100:101]
	v_lshl_add_u64 v[80:81], v[88:89], 0, v[156:157]
	s_waitcnt lgkmcnt(0)
	global_store_dwordx4 v[80:81], v[84:87], off nt
	v_lshlrev_b32_e32 v80, 16, v132
	v_and_b32_e32 v81, 0xffff0000, v132
	v_pk_add_f32 v[76:77], v[76:77], v[80:81]
	v_lshlrev_b32_e32 v80, 16, v133
	v_and_b32_e32 v81, 0xffff0000, v133
	v_pk_add_f32 v[78:79], v[78:79], v[80:81]
	v_lshlrev_b32_e32 v80, 16, v134
	v_and_b32_e32 v81, 0xffff0000, v134
	v_pk_add_f32 v[82:83], v[72:73], v[80:81]
	v_lshlrev_b32_e32 v80, 16, v128
	v_and_b32_e32 v81, 0xffff0000, v128
	v_pk_add_f32 v[86:87], v[68:69], v[80:81]
	v_lshlrev_b32_e32 v68, 16, v129
	v_and_b32_e32 v69, 0xffff0000, v129
	v_lshlrev_b32_e32 v72, 16, v135
	v_and_b32_e32 v73, 0xffff0000, v135
	v_pk_add_f32 v[96:97], v[70:71], v[68:69]
	v_lshlrev_b32_e32 v68, 16, v130
	v_and_b32_e32 v69, 0xffff0000, v130
	v_pk_add_f32 v[84:85], v[74:75], v[72:73]
	v_pk_add_f32 v[98:99], v[64:65], v[68:69]
	v_lshlrev_b32_e32 v64, 16, v131
	v_and_b32_e32 v65, 0xffff0000, v131
	v_cvt_pk_bf16_f32 v72, v76, v77
	v_cvt_pk_bf16_f32 v73, v78, v79
	v_cvt_pk_bf16_f32 v74, v82, v83
	v_cvt_pk_bf16_f32 v75, v84, v85
	v_pk_add_f32 v[100:101], v[66:67], v[64:65]
	s_ashr_i32 s37, s36, 31
	s_waitcnt lgkmcnt(0)
	s_barrier
	v_cvt_pk_bf16_f32 v64, v86, v87
	v_cvt_pk_bf16_f32 v65, v96, v97
	v_cvt_pk_bf16_f32 v66, v98, v99
	v_cvt_pk_bf16_f32 v67, v100, v101
	s_lshl_b64 s[36:37], s[36:37], 11
	ds_write_b128 v181, v[72:75]
	ds_write_b128 v181, v[64:67] offset:256
	s_add_u32 s23, s58, s36
	s_waitcnt lgkmcnt(0)
	s_barrier
	s_addc_u32 s25, s59, s37
	ds_read_b128 v[64:67], v182
	ds_read_b128 v[68:71], v182 offset:4224
	s_add_u32 s36, s23, s30
	s_addc_u32 s37, s25, s31
	v_lshl_add_u64 v[72:73], s[36:37], 0, v[152:153]
	v_lshl_add_u64 v[74:75], v[72:73], 0, v[154:155]
	v_add_u32_e32 v80, 0x80, v170
	s_waitcnt lgkmcnt(1)
	global_store_dwordx4 v[74:75], v[64:67], off nt
	v_ashrrev_i32_e32 v81, 31, v80
	v_xor_b32_e32 v113, 32, v183
	v_lshl_add_u64 v[64:65], v[72:73], 0, v[156:157]
	s_waitcnt lgkmcnt(0)
	global_store_dwordx4 v[64:65], v[68:71], off nt
	v_lshlrev_b64 v[64:65], 11, v[80:81]
	s_waitcnt lgkmcnt(0)
	s_barrier
	v_lshl_add_u64 v[66:67], v[172:173], 0, v[64:65]
	global_load_dwordx4 v[88:91], v[66:67], off
	v_add_f32_e32 v66, v92, v102
	v_add_f32_e32 v66, v93, v66
	v_add_f32_e32 v66, v94, v66
	v_cmp_lt_i32_e32 vcc, v113, v115
	v_add_f32_e32 v66, v95, v66
	v_lshl_add_u64 v[64:65], v[174:175], 0, v[64:65]
	v_cndmask_b32_e32 v113, v183, v113, vcc
	v_add_f32_e32 v66, v104, v66
	v_add_co_u32_e32 v64, vcc, s62, v64
	v_pk_mul_f32 v[110:111], v[108:109], v[108:109]
	v_add_f32_e32 v66, v105, v66
	v_addc_co_u32_e32 v65, vcc, 0, v65, vcc
	v_add_f32_e32 v66, v110, v66
	global_load_dwordx4 v[92:95], v[64:65], off offset:256
	v_add_f32_e32 v102, v111, v66
	v_pk_mul_f32 v[66:67], v[76:77], v[76:77]
	v_pk_mul_f32 v[68:69], v[78:79], v[78:79]
	v_add_f32_e32 v66, v66, v67
	v_add_f32_e32 v66, v68, v66
	v_pk_mul_f32 v[70:71], v[82:83], v[82:83]
	v_add_f32_e32 v66, v69, v66
	v_add_f32_e32 v66, v70, v66
	v_pk_mul_f32 v[72:73], v[84:85], v[84:85]
	v_add_f32_e32 v66, v71, v66
	v_add_f32_e32 v66, v72, v66
	v_pk_mul_f32 v[74:75], v[86:87], v[86:87]
	v_add_f32_e32 v66, v73, v66
	v_add_f32_e32 v66, v74, v66
	v_pk_mul_f32 v[64:65], v[96:97], v[96:97]
	v_add_f32_e32 v66, v75, v66
	v_add_f32_e32 v64, v64, v66
	v_pk_mul_f32 v[76:77], v[98:99], v[98:99]
	v_add_f32_e32 v64, v65, v64
	v_add_f32_e32 v64, v76, v64
	v_pk_mul_f32 v[78:79], v[100:101], v[100:101]
	v_add_f32_e32 v64, v77, v64
	v_add_f32_e32 v64, v78, v64
	v_add_f32_e32 v64, v79, v64
	ds_bpermute_b32 v65, v114, v64
	ds_bpermute_b32 v103, v114, v102
	s_add_i32 s36, s34, 0x80
	s_ashr_i32 s37, s36, 31
	s_lshl_b64 s[36:37], s[36:37], 11
	s_waitcnt lgkmcnt(1)
	v_add_f32_e32 v86, v64, v65
	v_add_u32_e32 v64, 0x90, v170
	v_ashrrev_i32_e32 v65, 31, v64
	v_lshlrev_b64 v[64:65], 11, v[64:65]
	v_lshl_add_u64 v[66:67], v[172:173], 0, v[64:65]
	v_lshl_add_u64 v[64:65], v[174:175], 0, v[64:65]
	v_add_co_u32_e32 v64, vcc, s62, v64
	s_waitcnt lgkmcnt(0)
	v_add_f32_e32 v84, v102, v103
	v_addc_co_u32_e32 v65, vcc, 0, v65, vcc
	global_load_dwordx4 v[96:99], v[66:67], off
	global_load_dwordx4 v[100:103], v[64:65], off offset:256
	v_add_u32_e32 v64, 0xa0, v170
	v_ashrrev_i32_e32 v65, 31, v64
	v_lshlrev_b64 v[64:65], 11, v[64:65]
	v_lshl_add_u64 v[66:67], v[172:173], 0, v[64:65]
	v_lshl_add_u64 v[64:65], v[174:175], 0, v[64:65]
	v_add_co_u32_e32 v64, vcc, s62, v64
	s_add_u32 s23, s58, s36
	s_nop 0
	v_addc_co_u32_e32 v65, vcc, 0, v65, vcc
	global_load_dwordx4 v[76:79], v[66:67], off
	global_load_dwordx4 v[72:75], v[64:65], off offset:256
	v_add_u32_e32 v64, 0xb0, v170
	v_ashrrev_i32_e32 v65, 31, v64
	v_lshlrev_b64 v[64:65], 11, v[64:65]
	v_lshl_add_u64 v[66:67], v[172:173], 0, v[64:65]
	v_lshl_add_u64 v[64:65], v[174:175], 0, v[64:65]
	v_add_co_u32_e32 v64, vcc, s62, v64
	s_addc_u32 s25, s59, s37
	s_nop 0
	v_addc_co_u32_e32 v65, vcc, 0, v65, vcc
	global_load_dwordx4 v[68:71], v[66:67], off
	s_nop 0
	global_load_dwordx4 v[64:67], v[64:65], off offset:256
	s_waitcnt vmcnt(7)
; #define LAS __attribute__((address_space(3)))
; __device__ __forceinline__ u32x4 pack8(const float (&f)[8]) { u32x4 w; w.x = pk2(f[0], f[1]); w.y = pk2(f[2], f[3]); w.z = pk2(f[4], f[5]); w.w = pk2(f[6], f[7]); return w; }
;     __device__ __forceinline__ void stage512(const u32x4 a, const u32x4 b, unsigned char* g0, size_t ldb, int wr, int wc, int fr, int fq) const {
;         LAS unsigned char* sb = lds + LDS_STG + wr * 8448;
;         *(LAS u32x4*)(sb + fr * 528 + wc * 64 + fq * 16) = a; *(LAS u32x4*)(sb + fr * 528 + 256 + wc * 64 + fq * 16) = b;
;         asm volatile("s_waitcnt lgkmcnt(0)" ::: "memory"); __builtin_amdgcn_s_barrier(); asm volatile("" ::: "memory");
;         const int l = fq * 16 + fr;
; #pragma unroll
;         for (int q = 0; q < 2; ++q) { const int rl = (q * 4 + wc) * 2 + (l >> 5); const u32x4 v = *(const LAS u32x4*)(sb + rl * 528 + (l & 31) * 16); *(u32x4*)(g0 + (size_t)rl * ldb + (l & 31) * 16) = v; }
;         asm volatile("s_waitcnt lgkmcnt(0)" ::: "memory"); __builtin_amdgcn_s_barrier(); asm volatile("" ::: "memory");
;     }
;     __device__ __forceinline__ float compute(const Pre& p, f32x4 (&acc)[2][2][4][2], const f32x4 (&cv)[2][2], const pg8::Unit& u, int ai, int m, int wr, int wc, int fr, int fq) const {
;     ...
;             } else if (MODE == EM_RES1) {
;                 const size_t o = (size_t)row * 1024 + u.pn * 256 + ct;
;                 float w[8], xr[8]; unpack8(p.a[bj], xr);
; #pragma unroll
;                 for (int j = 0; j < 8; ++j) { w[j] = v[j] + xr[j]; ssq += w[j] * w[j]; }
;                 pk[bj] = pack8(w); (void)o;
	v_lshlrev_b32_e32 v104, 16, v88
	v_and_b32_e32 v105, 0xffff0000, v88
	v_lshlrev_b32_e32 v106, 16, v90
	v_and_b32_e32 v107, 0xffff0000, v90
	v_pk_add_f32 v[60:61], v[60:61], v[104:105]
	v_lshlrev_b32_e32 v88, 16, v89
	v_and_b32_e32 v89, 0xffff0000, v89
	v_pk_add_f32 v[106:107], v[56:57], v[106:107]
	v_lshlrev_b32_e32 v56, 16, v91
	v_and_b32_e32 v57, 0xffff0000, v91
	v_pk_mul_f32 v[104:105], v[60:61], v[60:61]
	v_pk_add_f32 v[62:63], v[62:63], v[88:89]
	v_pk_add_f32 v[90:91], v[58:59], v[56:57]
	v_pk_mul_f32 v[88:89], v[62:63], v[62:63]
	v_pk_mul_f32 v[110:111], v[90:91], v[90:91]
	v_cvt_pk_bf16_f32 v59, v90, v91
	s_waitcnt vmcnt(6)
	v_lshlrev_b32_e32 v90, 16, v94
	v_and_b32_e32 v91, 0xffff0000, v94
	v_add_f32_e32 v94, v104, v105
	v_add_f32_e32 v88, v88, v94
	v_pk_mul_f32 v[108:109], v[106:107], v[106:107]
	v_add_f32_e32 v88, v89, v88
	v_add_f32_e32 v88, v108, v88
	v_cvt_pk_bf16_f32 v56, v60, v61
	v_lshlrev_b32_e32 v60, 16, v92
	v_and_b32_e32 v61, 0xffff0000, v92
	v_add_f32_e32 v88, v109, v88
	v_pk_add_f32 v[52:53], v[52:53], v[60:61]
	v_add_f32_e32 v88, v110, v88
	v_cvt_pk_bf16_f32 v57, v62, v63
	v_pk_mul_f32 v[60:61], v[52:53], v[52:53]
	v_lshlrev_b32_e32 v62, 16, v93
	v_and_b32_e32 v63, 0xffff0000, v93
	v_add_f32_e32 v88, v111, v88
	v_pk_add_f32 v[54:55], v[54:55], v[62:63]
	v_add_f32_e32 v60, v60, v88
	v_pk_mul_f32 v[62:63], v[54:55], v[54:55]
	v_add_f32_e32 v60, v61, v60
	v_pk_add_f32 v[90:91], v[48:49], v[90:91]
	v_add_f32_e32 v60, v62, v60
	v_pk_mul_f32 v[48:49], v[90:91], v[90:91]
	v_lshlrev_b32_e32 v92, 16, v95
	v_and_b32_e32 v93, 0xffff0000, v95
	v_add_f32_e32 v60, v63, v60
	v_pk_add_f32 v[92:93], v[50:51], v[92:93]
	v_add_f32_e32 v48, v48, v60
	v_pk_mul_f32 v[50:51], v[92:93], v[92:93]
	v_add_f32_e32 v48, v49, v48
	v_cvt_pk_bf16_f32 v58, v106, v107
	v_add_f32_e32 v48, v50, v48
	v_add_f32_e32 v60, v51, v48
	v_cvt_pk_bf16_f32 v48, v52, v53
	v_cvt_pk_bf16_f32 v49, v54, v55
	v_cvt_pk_bf16_f32 v50, v90, v91
	v_cvt_pk_bf16_f32 v51, v92, v93
	ds_write_b128 v181, v[56:59]
	ds_write_b128 v181, v[48:51] offset:256
	s_waitcnt lgkmcnt(0)
	s_barrier
	ds_read_b128 v[48:51], v182
	ds_read_b128 v[52:55], v182 offset:4224
	s_add_u32 s36, s23, s30
	s_addc_u32 s37, s25, s31
	v_lshl_add_u64 v[56:57], s[36:37], 0, v[152:153]
	v_lshl_add_u64 v[58:59], v[56:57], 0, v[154:155]
	s_waitcnt lgkmcnt(1)
	global_store_dwordx4 v[58:59], v[48:51], off nt
	ds_bpermute_b32 v50, v114, v60
	s_add_i32 s36, s34, 0x90
	v_lshl_add_u64 v[48:49], v[56:57], 0, v[156:157]
	s_waitcnt lgkmcnt(1)
	global_store_dwordx4 v[48:49], v[52:55], off nt
	s_waitcnt vmcnt(7)
	v_and_b32_e32 v51, 0xffff0000, v96
	s_waitcnt lgkmcnt(0)
	v_add_f32_e32 v48, v60, v50
	v_lshlrev_b32_e32 v50, 16, v96
	v_pk_add_f32 v[44:45], v[44:45], v[50:51]
	v_lshlrev_b32_e32 v52, 16, v97
	v_and_b32_e32 v53, 0xffff0000, v97
	v_pk_mul_f32 v[50:51], v[44:45], v[44:45]
	v_pk_add_f32 v[46:47], v[46:47], v[52:53]
	v_lshlrev_b32_e32 v54, 16, v98
	v_pk_mul_f32 v[52:53], v[46:47], v[46:47]
	v_and_b32_e32 v55, 0xffff0000, v98
	v_add_f32_e32 v50, v50, v51
	v_pk_add_f32 v[54:55], v[40:41], v[54:55]
	v_add_f32_e32 v50, v52, v50
	v_pk_mul_f32 v[56:57], v[54:55], v[54:55]
	v_lshlrev_b32_e32 v40, 16, v99
	v_and_b32_e32 v41, 0xffff0000, v99
	v_add_f32_e32 v50, v53, v50
	v_pk_add_f32 v[58:59], v[42:43], v[40:41]
	v_add_f32_e32 v50, v56, v50
	v_pk_mul_f32 v[60:61], v[58:59], v[58:59]
	v_cvt_pk_bf16_f32 v40, v44, v45
	s_waitcnt vmcnt(6)
	v_lshlrev_b32_e32 v44, 16, v100
	v_and_b32_e32 v45, 0xffff0000, v100
	v_add_f32_e32 v50, v57, v50
	v_pk_add_f32 v[36:37], v[36:37], v[44:45]
	v_add_f32_e32 v50, v60, v50
	v_cvt_pk_bf16_f32 v41, v46, v47
	v_pk_mul_f32 v[44:45], v[36:37], v[36:37]
	v_lshlrev_b32_e32 v46, 16, v101
	v_and_b32_e32 v47, 0xffff0000, v101
	v_add_f32_e32 v50, v61, v50
	v_pk_add_f32 v[38:39], v[38:39], v[46:47]
	v_add_f32_e32 v44, v44, v50
	v_cvt_pk_bf16_f32 v42, v54, v55
	v_pk_mul_f32 v[46:47], v[38:39], v[38:39]
	v_lshlrev_b32_e32 v54, 16, v102
	v_and_b32_e32 v55, 0xffff0000, v102
	v_add_f32_e32 v44, v45, v44
	v_pk_add_f32 v[54:55], v[32:33], v[54:55]
	v_add_f32_e32 v44, v46, v44
	v_cvt_pk_bf16_f32 v43, v58, v59
	v_pk_mul_f32 v[32:33], v[54:55], v[54:55]
	v_lshlrev_b32_e32 v58, 16, v103
	v_and_b32_e32 v59, 0xffff0000, v103
	v_add_f32_e32 v44, v47, v44
	v_pk_add_f32 v[58:59], v[34:35], v[58:59]
	v_add_f32_e32 v32, v32, v44
	v_pk_mul_f32 v[34:35], v[58:59], v[58:59]
	v_add_f32_e32 v32, v33, v32
	v_add_f32_e32 v32, v34, v32
	s_ashr_i32 s37, s36, 31
	s_waitcnt lgkmcnt(0)
	s_barrier
	v_add_f32_e32 v44, v35, v32
	v_cvt_pk_bf16_f32 v32, v36, v37
	v_cvt_pk_bf16_f32 v33, v38, v39
	v_cvt_pk_bf16_f32 v34, v54, v55
	v_cvt_pk_bf16_f32 v35, v58, v59
	s_lshl_b64 s[36:37], s[36:37], 11
	ds_write_b128 v181, v[40:43]
	ds_write_b128 v181, v[32:35] offset:256
	s_add_u32 s23, s58, s36
	s_waitcnt lgkmcnt(0)
	s_barrier
; #define LAS __attribute__((address_space(3)))
; __device__ __forceinline__ u32x4 pack8(const float (&f)[8]) { u32x4 w; w.x = pk2(f[0], f[1]); w.y = pk2(f[2], f[3]); w.z = pk2(f[4], f[5]); w.w = pk2(f[6], f[7]); return w; }
;     __device__ __forceinline__ void stage512(const u32x4 a, const u32x4 b, unsigned char* g0, size_t ldb, int wr, int wc, int fr, int fq) const {
;         LAS unsigned char* sb = lds + LDS_STG + wr * 8448;
;         *(LAS u32x4*)(sb + fr * 528 + wc * 64 + fq * 16) = a; *(LAS u32x4*)(sb + fr * 528 + 256 + wc * 64 + fq * 16) = b;
;         asm volatile("s_waitcnt lgkmcnt(0)" ::: "memory"); __builtin_amdgcn_s_barrier(); asm volatile("" ::: "memory");
;         const int l = fq * 16 + fr;
; #pragma unroll
;         for (int q = 0; q < 2; ++q) { const int rl = (q * 4 + wc) * 2 + (l >> 5); const u32x4 v = *(const LAS u32x4*)(sb + rl * 528 + (l & 31) * 16); *(u32x4*)(g0 + (size_t)rl * ldb + (l & 31) * 16) = v; }
;         asm volatile("s_waitcnt lgkmcnt(0)" ::: "memory"); __builtin_amdgcn_s_barrier(); asm volatile("" ::: "memory");
;     }
;     __device__ __forceinline__ float compute(const Pre& p, f32x4 (&acc)[2][2][4][2], const f32x4 (&cv)[2][2], const pg8::Unit& u, int ai, int m, int wr, int wc, int fr, int fq) const {
;     ...
;             } else if (MODE == EM_RES1) {
;                 const size_t o = (size_t)row * 1024 + u.pn * 256 + ct;
;                 float w[8], xr[8]; unpack8(p.a[bj], xr);
; #pragma unroll
;                 for (int j = 0; j < 8; ++j) { w[j] = v[j] + xr[j]; ssq += w[j] * w[j]; }
;                 pk[bj] = pack8(w); (void)o;
	s_addc_u32 s25, s59, s37
	ds_read_b128 v[32:35], v182
	ds_read_b128 v[36:39], v182 offset:4224
	s_add_u32 s36, s23, s30
	s_addc_u32 s37, s25, s31
	v_lshl_add_u64 v[40:41], s[36:37], 0, v[152:153]
	v_lshl_add_u64 v[42:43], v[40:41], 0, v[154:155]
	s_waitcnt lgkmcnt(1)
	global_store_dwordx4 v[42:43], v[32:35], off nt
	ds_bpermute_b32 v34, v114, v44
	s_add_i32 s36, s34, 0xa0
	v_lshl_add_u64 v[32:33], v[40:41], 0, v[156:157]
	s_waitcnt lgkmcnt(1)
	global_store_dwordx4 v[32:33], v[36:39], off nt
	s_waitcnt vmcnt(7)
	v_and_b32_e32 v35, 0xffff0000, v76
	s_waitcnt lgkmcnt(0)
	v_add_f32_e32 v32, v44, v34
	v_lshlrev_b32_e32 v34, 16, v76
	v_pk_add_f32 v[28:29], v[28:29], v[34:35]
	v_lshlrev_b32_e32 v36, 16, v77
	v_and_b32_e32 v37, 0xffff0000, v77
	v_pk_mul_f32 v[34:35], v[28:29], v[28:29]
	v_pk_add_f32 v[30:31], v[30:31], v[36:37]
	v_lshlrev_b32_e32 v38, 16, v78
	v_pk_mul_f32 v[36:37], v[30:31], v[30:31]
	v_and_b32_e32 v39, 0xffff0000, v78
	v_add_f32_e32 v34, v34, v35
	v_pk_add_f32 v[38:39], v[24:25], v[38:39]
	v_add_f32_e32 v34, v36, v34
	v_pk_mul_f32 v[40:41], v[38:39], v[38:39]
	v_lshlrev_b32_e32 v24, 16, v79
	v_and_b32_e32 v25, 0xffff0000, v79
	v_add_f32_e32 v34, v37, v34
	v_pk_add_f32 v[42:43], v[26:27], v[24:25]
	v_add_f32_e32 v34, v40, v34
	v_pk_mul_f32 v[44:45], v[42:43], v[42:43]
	v_cvt_pk_bf16_f32 v24, v28, v29
	s_waitcnt vmcnt(6)
	v_lshlrev_b32_e32 v28, 16, v72
	v_and_b32_e32 v29, 0xffff0000, v72
	v_add_f32_e32 v34, v41, v34
	v_pk_add_f32 v[20:21], v[20:21], v[28:29]
	v_add_f32_e32 v34, v44, v34
	v_cvt_pk_bf16_f32 v25, v30, v31
	v_pk_mul_f32 v[28:29], v[20:21], v[20:21]
	v_lshlrev_b32_e32 v30, 16, v73
	v_and_b32_e32 v31, 0xffff0000, v73
	v_add_f32_e32 v34, v45, v34
	v_pk_add_f32 v[22:23], v[22:23], v[30:31]
	v_add_f32_e32 v28, v28, v34
	v_cvt_pk_bf16_f32 v26, v38, v39
	v_pk_mul_f32 v[30:31], v[22:23], v[22:23]
	v_lshlrev_b32_e32 v38, 16, v74
	v_and_b32_e32 v39, 0xffff0000, v74
	v_add_f32_e32 v28, v29, v28
	v_pk_add_f32 v[38:39], v[16:17], v[38:39]
	v_add_f32_e32 v28, v30, v28
	v_cvt_pk_bf16_f32 v27, v42, v43
	v_pk_mul_f32 v[16:17], v[38:39], v[38:39]
	v_lshlrev_b32_e32 v42, 16, v75
	v_and_b32_e32 v43, 0xffff0000, v75
	v_add_f32_e32 v28, v31, v28
	v_pk_add_f32 v[42:43], v[18:19], v[42:43]
	v_add_f32_e32 v16, v16, v28
	v_pk_mul_f32 v[18:19], v[42:43], v[42:43]
	v_add_f32_e32 v16, v17, v16
	v_add_f32_e32 v16, v18, v16
	s_ashr_i32 s37, s36, 31
	s_waitcnt lgkmcnt(0)
	s_barrier
	v_add_f32_e32 v28, v19, v16
	v_cvt_pk_bf16_f32 v16, v20, v21
	v_cvt_pk_bf16_f32 v17, v22, v23
	v_cvt_pk_bf16_f32 v18, v38, v39
	v_cvt_pk_bf16_f32 v19, v42, v43
	s_lshl_b64 s[36:37], s[36:37], 11
	ds_write_b128 v181, v[24:27]
	ds_write_b128 v181, v[16:19] offset:256
	s_add_u32 s23, s58, s36
	s_waitcnt lgkmcnt(0)
	s_barrier
; #define LAS __attribute__((address_space(3)))
;     __device__ __forceinline__ void stage512(const u32x4 a, const u32x4 b, unsigned char* g0, size_t ldb, int wr, int wc, int fr, int fq) const {
;         LAS unsigned char* sb = lds + LDS_STG + wr * 8448;
;         *(LAS u32x4*)(sb + fr * 528 + wc * 64 + fq * 16) = a; *(LAS u32x4*)(sb + fr * 528 + 256 + wc * 64 + fq * 16) = b;
;         asm volatile("s_waitcnt lgkmcnt(0)" ::: "memory"); __builtin_amdgcn_s_barrier(); asm volatile("" ::: "memory");
;         const int l = fq * 16 + fr;
; #pragma unroll
;         for (int q = 0; q < 2; ++q) { const int rl = (q * 4 + wc) * 2 + (l >> 5); const u32x4 v = *(const LAS u32x4*)(sb + rl * 528 + (l & 31) * 16); *(u32x4*)(g0 + (size_t)rl * ldb + (l & 31) * 16) = v; }
;         asm volatile("s_waitcnt lgkmcnt(0)" ::: "memory"); __builtin_amdgcn_s_barrier(); asm volatile("" ::: "memory");
;     }
;     __device__ __forceinline__ float compute(const Pre& p, f32x4 (&acc)[2][2][4][2], const f32x4 (&cv)[2][2], const pg8::Unit& u, int ai, int m, int wr, int wc, int fr, int fq) const {
;     ...
;         if (MODE == EM_PLAIN) stage512(pk[0], pk[1], (unsigned char*)O + (trow * ldc + u.pn * 256) * 2, (size_t)ldc * 2, wr, wc, fr, fq);
;         if (MODE == EM_MERGE) stage512(pk[0], pk[1], ws + WS_MRG + (trow * 1024 + u.pn * 256) * 2, 2048, wr, wc, fr, fq);
;         if (MODE == EM_RES1) stage512(pk[0], pk[1], ws + WS_H1B + (trow * 1024 + u.pn * 256) * 2, 2048, wr, wc, fr, fq);
;         if (MODE == EM_RES1 || MODE == EM_RES2) { ssq += __shfl_xor(ssq, 16); ssq += __shfl_xor(ssq, 32); }
;         return ssq;
;     }
;     __device__ __forceinline__ void operator()(f32x4 (&acc)[2][2][4][2], const pg8::Unit& u, int wr, int wc, int fr, int fq) const {
;         f32x4 cv[2][2];
; #pragma unroll
;         for (int bj = 0; bj < 2; ++bj)
; #pragma unroll
;             for (int q = 0; q < 2; ++q) cv[bj][q] = (f32x4){0.f, 0.f, 0.f, 0.f};
;         if (MODE == EM_PROJ) { if ((u.pn >> 2) == 1) {
; #pragma unroll
;             for (int bj = 0; bj < 2; ++bj) { const float* lb = (const float*)(ws + WS_LB) + (u.pn & 3) * 256 + bj * 128 + wc * 32 + fq * 8; cv[bj][0] = *(const f32x4*)lb; cv[bj][1] = *(const f32x4*)(lb + 4); } } }
;         if (MODE == EM_GLU) { const int col = u.pn * 128 + wc * 32 + fq * 8;
	s_addc_u32 s25, s59, s37
	ds_read_b128 v[16:19], v182
	ds_read_b128 v[20:23], v182 offset:4224
	s_add_u32 s36, s23, s30
	s_addc_u32 s37, s25, s31
	v_lshl_add_u64 v[24:25], s[36:37], 0, v[152:153]
	v_lshl_add_u64 v[26:27], v[24:25], 0, v[154:155]
	s_waitcnt lgkmcnt(1)
	global_store_dwordx4 v[26:27], v[16:19], off nt
	ds_bpermute_b32 v18, v114, v28
	s_addk_i32 s34, 0xb0
	v_lshl_add_u64 v[16:17], v[24:25], 0, v[156:157]
	s_waitcnt lgkmcnt(1)
	global_store_dwordx4 v[16:17], v[20:23], off nt
	s_waitcnt vmcnt(7)
	v_and_b32_e32 v19, 0xffff0000, v68
	s_waitcnt lgkmcnt(0)
	v_add_f32_e32 v16, v28, v18
	v_lshlrev_b32_e32 v18, 16, v68
	v_pk_add_f32 v[12:13], v[12:13], v[18:19]
	v_lshlrev_b32_e32 v20, 16, v69
	v_and_b32_e32 v21, 0xffff0000, v69
	v_pk_mul_f32 v[18:19], v[12:13], v[12:13]
	v_pk_add_f32 v[14:15], v[14:15], v[20:21]
	v_lshlrev_b32_e32 v22, 16, v70
	v_pk_mul_f32 v[20:21], v[14:15], v[14:15]
	v_and_b32_e32 v23, 0xffff0000, v70
	v_add_f32_e32 v18, v18, v19
	v_pk_add_f32 v[22:23], v[8:9], v[22:23]
	v_add_f32_e32 v18, v20, v18
	v_pk_mul_f32 v[24:25], v[22:23], v[22:23]
	v_lshlrev_b32_e32 v8, 16, v71
	v_and_b32_e32 v9, 0xffff0000, v71
	v_add_f32_e32 v18, v21, v18
	v_pk_add_f32 v[26:27], v[10:11], v[8:9]
	v_add_f32_e32 v18, v24, v18
	v_pk_mul_f32 v[28:29], v[26:27], v[26:27]
	v_cvt_pk_bf16_f32 v8, v12, v13
	s_waitcnt vmcnt(6)
	v_lshlrev_b32_e32 v12, 16, v64
	v_and_b32_e32 v13, 0xffff0000, v64
	v_add_f32_e32 v18, v25, v18
	v_pk_add_f32 v[4:5], v[4:5], v[12:13]
	v_add_f32_e32 v18, v28, v18
	v_cvt_pk_bf16_f32 v9, v14, v15
	v_pk_mul_f32 v[12:13], v[4:5], v[4:5]
	v_lshlrev_b32_e32 v14, 16, v65
	v_and_b32_e32 v15, 0xffff0000, v65
	v_add_f32_e32 v18, v29, v18
	v_pk_add_f32 v[6:7], v[6:7], v[14:15]
	v_add_f32_e32 v12, v12, v18
	v_cvt_pk_bf16_f32 v10, v22, v23
	v_pk_mul_f32 v[14:15], v[6:7], v[6:7]
	v_lshlrev_b32_e32 v22, 16, v66
	v_and_b32_e32 v23, 0xffff0000, v66
	v_add_f32_e32 v12, v13, v12
	v_pk_add_f32 v[22:23], v[0:1], v[22:23]
	v_add_f32_e32 v12, v14, v12
	v_cvt_pk_bf16_f32 v11, v26, v27
	v_pk_mul_f32 v[0:1], v[22:23], v[22:23]
	v_lshlrev_b32_e32 v26, 16, v67
	v_and_b32_e32 v27, 0xffff0000, v67
	v_add_f32_e32 v12, v15, v12
	v_pk_add_f32 v[26:27], v[2:3], v[26:27]
	v_add_f32_e32 v0, v0, v12
	v_pk_mul_f32 v[2:3], v[26:27], v[26:27]
	v_add_f32_e32 v0, v1, v0
	v_add_f32_e32 v0, v2, v0
	s_ashr_i32 s35, s34, 31
	s_waitcnt lgkmcnt(0)
	s_barrier
	v_add_f32_e32 v12, v3, v0
	v_cvt_pk_bf16_f32 v0, v4, v5
	v_cvt_pk_bf16_f32 v1, v6, v7
	v_cvt_pk_bf16_f32 v2, v22, v23
	v_cvt_pk_bf16_f32 v3, v26, v27
	s_lshl_b64 s[34:35], s[34:35], 11
	ds_write_b128 v181, v[8:11]
	ds_write_b128 v181, v[0:3] offset:256
	s_add_u32 s23, s58, s34
	s_waitcnt lgkmcnt(0)
	s_barrier
	s_addc_u32 s25, s59, s35
	ds_read_b128 v[0:3], v182
	ds_read_b128 v[4:7], v182 offset:4224
	s_add_u32 s30, s23, s30
	s_addc_u32 s31, s25, s31
	v_lshl_add_u64 v[8:9], s[30:31], 0, v[152:153]
	v_lshl_add_u64 v[10:11], v[8:9], 0, v[154:155]
	ds_bpermute_b32 v117, v114, v116
	s_waitcnt lgkmcnt(2)
	global_store_dwordx4 v[10:11], v[0:3], off nt
	ds_bpermute_b32 v2, v114, v12
	v_lshlrev_b32_e32 v115, 2, v113
	v_lshl_add_u64 v[0:1], v[8:9], 0, v[156:157]
	s_waitcnt lgkmcnt(1)
	v_add_f32_e32 v82, v116, v117
	global_store_dwordx4 v[0:1], v[4:7], off nt
	s_waitcnt lgkmcnt(0)
	v_add_f32_e32 v0, v12, v2
	ds_bpermute_b32 v113, v115, v112
	ds_bpermute_b32 v83, v115, v82
	ds_bpermute_b32 v85, v115, v84
	ds_bpermute_b32 v87, v115, v86
	ds_bpermute_b32 v49, v115, v48
	ds_bpermute_b32 v33, v115, v32
	ds_bpermute_b32 v17, v115, v16
	ds_bpermute_b32 v1, v115, v0
	s_waitcnt lgkmcnt(0)
	s_barrier
	s_and_saveexec_b64 s[30:31], s[4:5]
	v_readlane_b32 s66, v255, 7
	v_readlane_b32 s67, v255, 8
	s_cbranch_execz .LBB0_1256
	s_waitcnt lgkmcnt(0)
	v_add_f32_e32 v4, v0, v1
	v_lshlrev_b64 v[0:1], 2, v[170:171]
	v_lshl_add_u64 v[2:3], s[20:21], 0, v[0:1]
	v_lshl_add_u64 v[0:1], s[92:93], 0, v[0:1]
	v_add_f32_e32 v10, v112, v113
	v_add_co_u32_e32 v0, vcc, 0x1f440000, v0
	v_add_f32_e32 v11, v82, v83
	global_atomic_add_f32 v[2:3], v10, off
	v_addc_co_u32_e32 v1, vcc, 0, v1, vcc
	v_add_f32_e32 v8, v86, v87
	v_add_f32_e32 v9, v84, v85
	global_atomic_add_f32 v[0:1], v11, off offset:64
	global_atomic_add_f32 v[0:1], v9, off offset:128
	global_atomic_add_f32 v[0:1], v8, off offset:192
	v_lshlrev_b64 v[0:1], 2, v[80:81]
	v_lshl_add_u64 v[2:3], s[20:21], 0, v[0:1]
	v_lshl_add_u64 v[0:1], s[92:93], 0, v[0:1]
	v_add_f32_e32 v7, v48, v49
	v_add_co_u32_e32 v0, vcc, 0x1f440000, v0
	v_add_f32_e32 v6, v32, v33
	global_atomic_add_f32 v[2:3], v7, off
	v_addc_co_u32_e32 v1, vcc, 0, v1, vcc
	v_add_f32_e32 v5, v16, v17
	global_atomic_add_f32 v[0:1], v6, off offset:64
	global_atomic_add_f32 v[0:1], v5, off offset:128
	global_atomic_add_f32 v[0:1], v4, off offset:192

; #define LAS __attribute__((address_space(3)))
; __device__ __forceinline__ u32x4 pack8(const float (&f)[8]) { u32x4 w; w.x = pk2(f[0], f[1]); w.y = pk2(f[2], f[3]); w.z = pk2(f[4], f[5]); w.w = pk2(f[6], f[7]); return w; }
;     __device__ __forceinline__ void stage512(const u32x4 a, const u32x4 b, unsigned char* g0, size_t ldb, int wr, int wc, int fr, int fq) const {
;         LAS unsigned char* sb = lds + LDS_STG + wr * 8448;
;         *(LAS u32x4*)(sb + fr * 528 + wc * 64 + fq * 16) = a; *(LAS u32x4*)(sb + fr * 528 + 256 + wc * 64 + fq * 16) = b;
;         asm volatile("s_waitcnt lgkmcnt(0)" ::: "memory"); __builtin_amdgcn_s_barrier(); asm volatile("" ::: "memory");
;         const int l = fq * 16 + fr;
; #pragma unroll
;         for (int q = 0; q < 2; ++q) { const int rl = (q * 4 + wc) * 2 + (l >> 5); const u32x4 v = *(const LAS u32x4*)(sb + rl * 528 + (l & 31) * 16); *(u32x4*)(g0 + (size_t)rl * ldb + (l & 31) * 16) = v; }
;         asm volatile("s_waitcnt lgkmcnt(0)" ::: "memory"); __builtin_amdgcn_s_barrier(); asm volatile("" ::: "memory");
;     }
;     __device__ __forceinline__ float compute(const Pre& p, f32x4 (&acc)[2][2][4][2], const f32x4 (&cv)[2][2], const pg8::Unit& u, int ai, int m, int wr, int wc, int fr, int fq) const {
;     ...
;             } else if (MODE == EM_PLAIN) {
;                 pk[bj] = pack8(v);
.LBB0_1280:
	s_lshl_b32 s17, s24, 8
	s_lshl_b32 s26, s25, 8
	s_add_i32 s24, s17, s3
	s_ashr_i32 s27, s26, 31
	v_cvt_pk_bf16_f32 v124, v124, v125
	v_cvt_pk_bf16_f32 v125, v126, v127
	v_cvt_pk_bf16_f32 v126, v120, v121
	v_cvt_pk_bf16_f32 v127, v122, v123
	s_ashr_i32 s25, s24, 31
	v_cvt_pk_bf16_f32 v116, v116, v117
	v_cvt_pk_bf16_f32 v117, v118, v119
	v_cvt_pk_bf16_f32 v118, v112, v113
	v_cvt_pk_bf16_f32 v119, v114, v115
	s_lshl_b64 s[28:29], s[24:25], 11
	s_lshl_b64 s[26:27], s[26:27], 1
	ds_write_b128 v150, v[124:127]
	ds_write_b128 v150, v[116:119] offset:256
	s_add_u32 s17, s56, s28
	s_waitcnt lgkmcnt(0)
	s_barrier
	s_addc_u32 s19, s57, s29
	ds_read_b128 v[112:115], v151
	ds_read_b128 v[116:119], v151 offset:4224
	s_add_u32 s28, s17, s26
	s_addc_u32 s29, s19, s27
	v_lshl_add_u64 v[120:121], s[28:29], 0, v[136:137]
	v_lshl_add_u64 v[122:123], v[120:121], 0, v[138:139]
	s_waitcnt lgkmcnt(0)
	global_store_dwordx4 v[122:123], v[112:115], off nt
	s_or_b32 s28, s24, 16
	v_cvt_pk_bf16_f32 v108, v108, v109
	v_lshl_add_u64 v[112:113], v[120:121], 0, v[140:141]
	global_store_dwordx4 v[112:113], v[116:119], off nt
	v_cvt_pk_bf16_f32 v109, v110, v111
	v_cvt_pk_bf16_f32 v110, v104, v105
	v_cvt_pk_bf16_f32 v111, v106, v107
	s_ashr_i32 s29, s28, 31
	s_waitcnt lgkmcnt(0)
	s_barrier
	v_cvt_pk_bf16_f32 v100, v100, v101
	v_cvt_pk_bf16_f32 v101, v102, v103
	v_cvt_pk_bf16_f32 v102, v96, v97
	v_cvt_pk_bf16_f32 v103, v98, v99
	s_lshl_b64 s[28:29], s[28:29], 11
	ds_write_b128 v150, v[108:111]
	ds_write_b128 v150, v[100:103] offset:256
	s_add_u32 s17, s56, s28
	s_waitcnt lgkmcnt(0)
	s_barrier
	s_addc_u32 s19, s57, s29
	ds_read_b128 v[96:99], v151
	ds_read_b128 v[100:103], v151 offset:4224
	s_add_u32 s28, s17, s26
	s_addc_u32 s29, s19, s27
	v_lshl_add_u64 v[104:105], s[28:29], 0, v[136:137]
	v_lshl_add_u64 v[106:107], v[104:105], 0, v[138:139]
	s_waitcnt lgkmcnt(0)
	global_store_dwordx4 v[106:107], v[96:99], off nt
	s_or_b32 s28, s24, 32
	v_cvt_pk_bf16_f32 v92, v92, v93
	v_lshl_add_u64 v[96:97], v[104:105], 0, v[140:141]
	global_store_dwordx4 v[96:97], v[100:103], off nt
	v_cvt_pk_bf16_f32 v93, v94, v95
	v_cvt_pk_bf16_f32 v94, v88, v89
	v_cvt_pk_bf16_f32 v95, v90, v91
	s_ashr_i32 s29, s28, 31
	s_waitcnt lgkmcnt(0)
	s_barrier
	v_cvt_pk_bf16_f32 v84, v84, v85
	v_cvt_pk_bf16_f32 v85, v86, v87
	v_cvt_pk_bf16_f32 v86, v80, v81
	v_cvt_pk_bf16_f32 v87, v82, v83
	s_lshl_b64 s[28:29], s[28:29], 11
	ds_write_b128 v150, v[92:95]
	ds_write_b128 v150, v[84:87] offset:256
	s_add_u32 s17, s56, s28
	s_waitcnt lgkmcnt(0)
	s_barrier
	s_addc_u32 s19, s57, s29
	ds_read_b128 v[80:83], v151
	ds_read_b128 v[84:87], v151 offset:4224
	s_add_u32 s28, s17, s26
	s_addc_u32 s29, s19, s27
	v_lshl_add_u64 v[88:89], s[28:29], 0, v[136:137]
	v_lshl_add_u64 v[90:91], v[88:89], 0, v[138:139]
	s_waitcnt lgkmcnt(0)
	global_store_dwordx4 v[90:91], v[80:83], off nt
	s_or_b32 s28, s24, 48
	v_cvt_pk_bf16_f32 v76, v76, v77
	v_lshl_add_u64 v[80:81], v[88:89], 0, v[140:141]
	global_store_dwordx4 v[80:81], v[84:87], off nt
	v_cvt_pk_bf16_f32 v77, v78, v79
	v_cvt_pk_bf16_f32 v78, v72, v73
	v_cvt_pk_bf16_f32 v79, v74, v75
	s_ashr_i32 s29, s28, 31
	s_waitcnt lgkmcnt(0)
	s_barrier
	v_cvt_pk_bf16_f32 v68, v68, v69
	v_cvt_pk_bf16_f32 v69, v70, v71
	v_cvt_pk_bf16_f32 v70, v64, v65
	v_cvt_pk_bf16_f32 v71, v66, v67
	s_lshl_b64 s[28:29], s[28:29], 11
	ds_write_b128 v150, v[76:79]
	ds_write_b128 v150, v[68:71] offset:256
	s_add_u32 s17, s56, s28
	s_waitcnt lgkmcnt(0)
	s_barrier
	s_addc_u32 s19, s57, s29
	ds_read_b128 v[64:67], v151
	ds_read_b128 v[68:71], v151 offset:4224
	s_add_u32 s28, s17, s26
	s_addc_u32 s29, s19, s27
	v_lshl_add_u64 v[72:73], s[28:29], 0, v[136:137]
	v_lshl_add_u64 v[74:75], v[72:73], 0, v[138:139]
	s_waitcnt lgkmcnt(0)
	global_store_dwordx4 v[74:75], v[64:67], off nt
	s_add_i32 s28, s24, 0x80
	v_cvt_pk_bf16_f32 v60, v60, v61
	v_lshl_add_u64 v[64:65], v[72:73], 0, v[140:141]
	global_store_dwordx4 v[64:65], v[68:71], off nt
	v_cvt_pk_bf16_f32 v61, v62, v63
	v_cvt_pk_bf16_f32 v62, v56, v57
	v_cvt_pk_bf16_f32 v63, v58, v59
	s_ashr_i32 s29, s28, 31
	s_waitcnt lgkmcnt(0)
	s_barrier
; #define LAS __attribute__((address_space(3)))
; __device__ __forceinline__ u32x4 pack8(const float (&f)[8]) { u32x4 w; w.x = pk2(f[0], f[1]); w.y = pk2(f[2], f[3]); w.z = pk2(f[4], f[5]); w.w = pk2(f[6], f[7]); return w; }
;     __device__ __forceinline__ void stage512(const u32x4 a, const u32x4 b, unsigned char* g0, size_t ldb, int wr, int wc, int fr, int fq) const {
;         LAS unsigned char* sb = lds + LDS_STG + wr * 8448;
;         *(LAS u32x4*)(sb + fr * 528 + wc * 64 + fq * 16) = a; *(LAS u32x4*)(sb + fr * 528 + 256 + wc * 64 + fq * 16) = b;
;         asm volatile("s_waitcnt lgkmcnt(0)" ::: "memory"); __builtin_amdgcn_s_barrier(); asm volatile("" ::: "memory");
;         const int l = fq * 16 + fr;
; #pragma unroll
;         for (int q = 0; q < 2; ++q) { const int rl = (q * 4 + wc) * 2 + (l >> 5); const u32x4 v = *(const LAS u32x4*)(sb + rl * 528 + (l & 31) * 16); *(u32x4*)(g0 + (size_t)rl * ldb + (l & 31) * 16) = v; }
;         asm volatile("s_waitcnt lgkmcnt(0)" ::: "memory"); __builtin_amdgcn_s_barrier(); asm volatile("" ::: "memory");
;     }
;     __device__ __forceinline__ float compute(const Pre& p, f32x4 (&acc)[2][2][4][2], const f32x4 (&cv)[2][2], const pg8::Unit& u, int ai, int m, int wr, int wc, int fr, int fq) const {
;     ...
;             } else if (MODE == EM_PLAIN) {
;                 pk[bj] = pack8(v);
	v_cvt_pk_bf16_f32 v52, v52, v53
	v_cvt_pk_bf16_f32 v53, v54, v55
	v_cvt_pk_bf16_f32 v54, v48, v49
	v_cvt_pk_bf16_f32 v55, v50, v51
	s_lshl_b64 s[28:29], s[28:29], 11
	ds_write_b128 v150, v[60:63]
	ds_write_b128 v150, v[52:55] offset:256
	s_add_u32 s17, s56, s28
	s_waitcnt lgkmcnt(0)
	s_barrier
	s_addc_u32 s19, s57, s29
	ds_read_b128 v[48:51], v151
	ds_read_b128 v[52:55], v151 offset:4224
	s_add_u32 s28, s17, s26
	s_addc_u32 s29, s19, s27
	v_lshl_add_u64 v[56:57], s[28:29], 0, v[136:137]
	v_lshl_add_u64 v[58:59], v[56:57], 0, v[138:139]
	s_waitcnt lgkmcnt(0)
	global_store_dwordx4 v[58:59], v[48:51], off nt
	s_add_i32 s28, s24, 0x90
	v_cvt_pk_bf16_f32 v44, v44, v45
	v_lshl_add_u64 v[48:49], v[56:57], 0, v[140:141]
	global_store_dwordx4 v[48:49], v[52:55], off nt
	v_cvt_pk_bf16_f32 v45, v46, v47
	v_cvt_pk_bf16_f32 v46, v40, v41
	v_cvt_pk_bf16_f32 v47, v42, v43
	s_ashr_i32 s29, s28, 31
	s_waitcnt lgkmcnt(0)
	s_barrier
	v_cvt_pk_bf16_f32 v36, v36, v37
	v_cvt_pk_bf16_f32 v37, v38, v39
	v_cvt_pk_bf16_f32 v38, v32, v33
	v_cvt_pk_bf16_f32 v39, v34, v35
	s_lshl_b64 s[28:29], s[28:29], 11
	ds_write_b128 v150, v[44:47]
	ds_write_b128 v150, v[36:39] offset:256
	s_add_u32 s17, s56, s28
	s_waitcnt lgkmcnt(0)
	s_barrier
	s_addc_u32 s19, s57, s29
	ds_read_b128 v[32:35], v151
	ds_read_b128 v[36:39], v151 offset:4224
	s_add_u32 s28, s17, s26
	s_addc_u32 s29, s19, s27
	v_lshl_add_u64 v[40:41], s[28:29], 0, v[136:137]
	v_lshl_add_u64 v[42:43], v[40:41], 0, v[138:139]
	s_waitcnt lgkmcnt(0)
	global_store_dwordx4 v[42:43], v[32:35], off nt
	s_add_i32 s28, s24, 0xa0
	v_cvt_pk_bf16_f32 v28, v28, v29
	v_lshl_add_u64 v[32:33], v[40:41], 0, v[140:141]
	global_store_dwordx4 v[32:33], v[36:39], off nt
	v_cvt_pk_bf16_f32 v29, v30, v31
	v_cvt_pk_bf16_f32 v30, v24, v25
	v_cvt_pk_bf16_f32 v31, v26, v27
	s_ashr_i32 s29, s28, 31
	s_waitcnt lgkmcnt(0)
	s_barrier
	v_cvt_pk_bf16_f32 v20, v20, v21
	v_cvt_pk_bf16_f32 v21, v22, v23
	v_cvt_pk_bf16_f32 v22, v16, v17
	v_cvt_pk_bf16_f32 v23, v18, v19
	s_lshl_b64 s[28:29], s[28:29], 11
	ds_write_b128 v150, v[28:31]
	ds_write_b128 v150, v[20:23] offset:256
	s_add_u32 s17, s56, s28
	s_waitcnt lgkmcnt(0)
	s_barrier
	s_addc_u32 s19, s57, s29
	ds_read_b128 v[16:19], v151
	ds_read_b128 v[20:23], v151 offset:4224
	s_add_u32 s28, s17, s26
	s_addc_u32 s29, s19, s27
	v_lshl_add_u64 v[24:25], s[28:29], 0, v[136:137]
	v_lshl_add_u64 v[26:27], v[24:25], 0, v[138:139]
	s_waitcnt lgkmcnt(0)
	global_store_dwordx4 v[26:27], v[16:19], off nt
	s_addk_i32 s24, 0xb0
	v_cvt_pk_bf16_f32 v12, v12, v13
	v_lshl_add_u64 v[16:17], v[24:25], 0, v[140:141]
	global_store_dwordx4 v[16:17], v[20:23], off nt
	v_cvt_pk_bf16_f32 v13, v14, v15
	v_cvt_pk_bf16_f32 v14, v8, v9
	v_cvt_pk_bf16_f32 v15, v10, v11
	s_ashr_i32 s25, s24, 31
	s_waitcnt lgkmcnt(0)
	s_barrier
	v_cvt_pk_bf16_f32 v4, v4, v5
	v_cvt_pk_bf16_f32 v5, v6, v7
	v_cvt_pk_bf16_f32 v6, v0, v1
	v_cvt_pk_bf16_f32 v7, v2, v3
	s_lshl_b64 s[24:25], s[24:25], 11
	ds_write_b128 v150, v[12:15]
	ds_write_b128 v150, v[4:7] offset:256
	s_add_u32 s17, s56, s24
	s_waitcnt lgkmcnt(0)
	s_barrier
	s_addc_u32 s19, s57, s25
	ds_read_b128 v[0:3], v151
	ds_read_b128 v[4:7], v151 offset:4224
	s_add_u32 s24, s17, s26
	s_addc_u32 s25, s19, s27
	v_lshl_add_u64 v[8:9], s[24:25], 0, v[136:137]
	v_lshl_add_u64 v[10:11], v[8:9], 0, v[138:139]
	s_waitcnt lgkmcnt(0)
	global_store_dwordx4 v[10:11], v[0:3], off nt
	s_andn2_b64 vcc, exec, s[4:5]
	s_mov_b64 s[4:5], -1
	v_lshl_add_u64 v[0:1], v[8:9], 0, v[140:141]
	global_store_dwordx4 v[0:1], v[4:7], off nt
	s_waitcnt lgkmcnt(0)
	s_barrier
	v_readlane_b32 s66, v255, 7
	v_readlane_b32 s67, v255, 8
	s_cbranch_vccnz .LBB0_1269
	s_andn2_b64 vcc, exec, s[6:7]
	s_cbranch_vccnz .LBB0_1268
	s_barrier
	s_branch .LBB0_1268
